# intra-wave reductions without LDS round trips: DPP + permlane16/32_swap all-reduce in the P0 norm pass and P2 light pass, permlane swaps for the residual-epilogue row-sum shuffles
# speedup vs baseline: 1.0096x; 1.0061x over previous
.LBB0_158:
	global_load_dwordx4 v[14:17], v[4:5], off offset:-3072
	global_load_dwordx4 v[18:21], v[4:5], off offset:-2048
	global_load_dwordx4 v[22:25], v[4:5], off offset:-1024
	global_load_dwordx4 v[26:29], v[4:5], off
	s_add_i32 s5, s5, s72
	v_lshl_add_u64 v[4:5], v[4:5], 0, s[2:3]
	s_cmp_lt_i32 s5, 0x8000
	s_waitcnt vmcnt(3)
	v_pk_mul_f32 v[34:35], v[16:17], v[16:17]
	v_pk_mul_f32 v[36:37], v[14:15], v[14:15]
	s_waitcnt vmcnt(2)
	v_pk_mul_f32 v[38:39], v[20:21], v[20:21]
	v_pk_mul_f32 v[40:41], v[18:19], v[18:19]
	v_pk_mov_b32 v[46:47], v[36:37], v[34:35] op_sel:[1,0]
	v_mov_b32_e32 v37, v35
	v_pk_mov_b32 v[34:35], v[40:41], v[38:39] op_sel:[1,0]
	v_mov_b32_e32 v41, v39
	s_waitcnt vmcnt(0)
	v_mul_f32_e32 v45, v26, v26
	v_mul_f32_e32 v42, v23, v23
	v_mul_f32_e32 v44, v25, v25
	v_pk_add_f32 v[36:37], v[46:47], v[36:37]
	v_pk_add_f32 v[34:35], v[34:35], v[40:41]
	v_mul_f32_e32 v48, v27, v27
	v_mul_f32_e32 v49, v28, v28
	v_mul_f32_e32 v50, v29, v29
	v_pk_fma_f32 v[38:39], v[22:23], v[22:23], v[42:43] op_sel_hi:[1,1,0]
	v_pk_fma_f32 v[42:43], v[24:25], v[24:25], v[44:45] op_sel_hi:[1,1,0]
	v_pk_add_f32 v[36:37], v[36:37], v[36:37] op_sel:[0,1] op_sel_hi:[1,0]
	v_pk_add_f32 v[34:35], v[34:35], v[34:35] op_sel:[0,1] op_sel_hi:[1,0]
	v_mov_b32_e32 v39, v49
	v_mov_b32_e32 v43, v50
	v_mov_b32_e32 v37, v45
	v_mov_b32_e32 v35, v48
	v_pk_add_f32 v[38:39], v[38:39], v[42:43]
	v_pk_add_f32 v[34:35], v[36:37], v[34:35]
	s_nop 0
	v_pk_add_f32 v[34:35], v[34:35], v[38:39]
	s_nop 0
	v_add_f32_e32 v34, v34, v35
	s_nop 1
	v_add_f32_dpp v34, v34, v34 quad_perm:[1,0,3,2] row_mask:0xf bank_mask:0xf
	s_nop 1
	v_add_f32_dpp v34, v34, v34 quad_perm:[2,3,0,1] row_mask:0xf bank_mask:0xf
	s_nop 1
	v_add_f32_dpp v34, v34, v34 row_half_mirror row_mask:0xf bank_mask:0xf
	s_nop 1
	v_add_f32_dpp v34, v34, v34 row_mirror row_mask:0xf bank_mask:0xf
	v_mov_b32_e32 v35, v34
	s_nop 1
	v_permlane16_swap_b32_e32 v34, v35
	v_add_f32_e32 v34, v34, v35
	v_mov_b32_e32 v35, v34
	s_nop 1
	v_permlane32_swap_b32_e32 v34, v35
	v_add_f32_e32 v34, v34, v35
	v_fmamk_f32 v34, v34, 0x3a800000, v13
	v_mul_f32_e32 v35, 0x4b800000, v34
	v_cmp_gt_f32_e32 vcc, s4, v34
	s_nop 1
	v_cndmask_b32_e32 v34, v34, v35, vcc
	v_rsq_f32_e32 v34, v34
	s_nop 0
	v_mul_f32_e32 v35, 0x45800000, v34
	v_cndmask_b32_e32 v34, v34, v35, vcc
	v_pk_mul_f32 v[14:15], v[14:15], v[34:35] op_sel_hi:[1,0]
	v_pk_mul_f32 v[16:17], v[16:17], v[34:35] op_sel_hi:[1,0]
	v_pk_mul_f32 v[14:15], v[52:53], v[14:15]
	v_pk_mul_f32 v[16:17], v[54:55], v[16:17]
	v_cvt_pk_bf16_f32 v14, v14, v15
	v_cvt_pk_bf16_f32 v15, v16, v17
	global_store_dwordx2 v[0:1], v[14:15], off
	v_pk_mul_f32 v[18:19], v[18:19], v[34:35] op_sel_hi:[1,0]
	v_pk_mul_f32 v[20:21], v[20:21], v[34:35] op_sel_hi:[1,0]
	v_pk_mul_f32 v[14:15], v[56:57], v[18:19]
	v_pk_mul_f32 v[16:17], v[58:59], v[20:21]
	v_cvt_pk_bf16_f32 v14, v14, v15
	v_cvt_pk_bf16_f32 v15, v16, v17
	global_store_dwordx2 v[0:1], v[14:15], off offset:512
	v_pk_mul_f32 v[18:19], v[22:23], v[34:35] op_sel_hi:[1,0]
	v_pk_mul_f32 v[20:21], v[24:25], v[34:35] op_sel_hi:[1,0]
	v_pk_mul_f32 v[14:15], v[60:61], v[18:19]
	v_pk_mul_f32 v[16:17], v[62:63], v[20:21]
	v_cvt_pk_bf16_f32 v14, v14, v15
	v_cvt_pk_bf16_f32 v15, v16, v17
	global_store_dwordx2 v[0:1], v[14:15], off offset:1024
	v_pk_mul_f32 v[18:19], v[26:27], v[34:35] op_sel_hi:[1,0]
	v_pk_mul_f32 v[20:21], v[28:29], v[34:35] op_sel_hi:[1,0]
	v_pk_mul_f32 v[14:15], v[64:65], v[18:19]
	v_pk_mul_f32 v[16:17], v[66:67], v[20:21]
	v_cvt_pk_bf16_f32 v14, v14, v15
	v_cvt_pk_bf16_f32 v15, v16, v17
	global_store_dwordx2 v[0:1], v[14:15], off offset:1536
	v_lshl_add_u64 v[0:1], v[0:1], 0, s[0:1]
	s_cbranch_scc1 .LBB0_158

.LBB0_374:
	s_or_b64 exec, exec, s[2:3]
	s_waitcnt vmcnt(0)
	v_lshlrev_b32_e32 v94, 16, v24
	v_and_b32_e32 v95, 0xffff0000, v24
	v_lshlrev_b32_e32 v82, 16, v25
	v_and_b32_e32 v83, 0xffff0000, v25
	v_lshlrev_b32_e32 v80, 16, v26
	v_and_b32_e32 v81, 0xffff0000, v26
	v_lshlrev_b32_e32 v24, 16, v27
	v_and_b32_e32 v25, 0xffff0000, v27
	v_lshlrev_b32_e32 v26, 16, v8
	v_and_b32_e32 v27, 0xffff0000, v8
	v_lshlrev_b32_e32 v8, 16, v9
	v_and_b32_e32 v9, 0xffff0000, v9
	v_lshlrev_b32_e32 v96, 16, v4
	v_and_b32_e32 v97, 0xffff0000, v4
	v_pk_add_f32 v[8:9], v[82:83], v[8:9]
	v_lshlrev_b32_e32 v4, 16, v5
	v_and_b32_e32 v5, 0xffff0000, v5
	v_pk_add_f32 v[4:5], v[8:9], v[4:5]
	v_lshlrev_b32_e32 v8, 16, v21
	v_and_b32_e32 v9, 0xffff0000, v21
	v_pk_add_f32 v[4:5], v[4:5], v[8:9]
	v_lshlrev_b32_e32 v8, 16, v13
	v_and_b32_e32 v9, 0xffff0000, v13
	v_pk_add_f32 v[4:5], v[4:5], v[8:9]
	v_lshlrev_b32_e32 v8, 16, v37
	v_and_b32_e32 v9, 0xffff0000, v37
	v_pk_add_f32 v[26:27], v[94:95], v[26:27]
	v_pk_add_f32 v[4:5], v[4:5], v[8:9]
	v_lshlrev_b32_e32 v8, 16, v29
	v_and_b32_e32 v9, 0xffff0000, v29
	v_pk_add_f32 v[26:27], v[26:27], v[96:97]
	v_lshlrev_b32_e32 v96, 16, v20
	v_and_b32_e32 v97, 0xffff0000, v20
	v_pk_add_f32 v[8:9], v[4:5], v[8:9]
	v_lshlrev_b32_e32 v4, 16, v10
	v_and_b32_e32 v5, 0xffff0000, v10
	v_pk_add_f32 v[26:27], v[26:27], v[96:97]
	v_lshlrev_b32_e32 v96, 16, v12
	v_and_b32_e32 v97, 0xffff0000, v12
	v_pk_add_f32 v[4:5], v[80:81], v[4:5]
	v_lshlrev_b32_e32 v12, 16, v6
	v_and_b32_e32 v13, 0xffff0000, v6
	v_pk_add_f32 v[4:5], v[4:5], v[12:13]
	v_lshlrev_b32_e32 v12, 16, v22
	v_and_b32_e32 v13, 0xffff0000, v22
	v_pk_add_f32 v[4:5], v[4:5], v[12:13]
	v_lshlrev_b32_e32 v12, 16, v14
	v_and_b32_e32 v13, 0xffff0000, v14
	v_pk_add_f32 v[4:5], v[4:5], v[12:13]
	v_lshlrev_b32_e32 v12, 16, v38
	v_and_b32_e32 v13, 0xffff0000, v38
	v_pk_add_f32 v[4:5], v[4:5], v[12:13]
	v_lshlrev_b32_e32 v12, 16, v30
	v_and_b32_e32 v13, 0xffff0000, v30
	v_pk_add_f32 v[12:13], v[4:5], v[12:13]
	v_lshlrev_b32_e32 v4, 16, v11
	v_and_b32_e32 v5, 0xffff0000, v11
	v_pk_add_f32 v[4:5], v[24:25], v[4:5]
	v_lshlrev_b32_e32 v6, 16, v7
	v_and_b32_e32 v7, 0xffff0000, v7
	v_pk_add_f32 v[4:5], v[4:5], v[6:7]
	v_lshlrev_b32_e32 v6, 16, v23
	v_and_b32_e32 v7, 0xffff0000, v23
	v_pk_add_f32 v[4:5], v[4:5], v[6:7]
	v_lshlrev_b32_e32 v6, 16, v15
	v_and_b32_e32 v7, 0xffff0000, v15
	v_lshlrev_b32_e32 v14, 16, v50
	v_and_b32_e32 v15, 0xffff0000, v50
	v_cvt_f32_i32_e32 v50, v92
	v_lshlrev_b32_e32 v20, 16, v51
	v_and_b32_e32 v21, 0xffff0000, v51
	v_pk_add_f32 v[26:27], v[26:27], v[96:97]
	v_div_scale_f32 v51, s[2:3], v50, v50, 1.0
	v_lshlrev_b32_e32 v96, 16, v36
	v_and_b32_e32 v97, 0xffff0000, v36
	v_pk_add_f32 v[4:5], v[4:5], v[6:7]
	v_lshlrev_b32_e32 v6, 16, v39
	v_and_b32_e32 v7, 0xffff0000, v39
	v_lshlrev_b32_e32 v38, 16, v60
	v_and_b32_e32 v39, 0xffff0000, v60
	v_rcp_f32_e32 v60, v51
	v_pk_add_f32 v[26:27], v[26:27], v[96:97]
	v_lshlrev_b32_e32 v96, 16, v28
	v_and_b32_e32 v97, 0xffff0000, v28
	v_pk_add_f32 v[4:5], v[4:5], v[6:7]
	v_lshlrev_b32_e32 v6, 16, v31
	v_and_b32_e32 v7, 0xffff0000, v31
	v_pk_add_f32 v[26:27], v[26:27], v[96:97]
	v_pk_add_f32 v[10:11], v[4:5], v[6:7]
	v_lshlrev_b32_e32 v4, 16, v48
	v_and_b32_e32 v5, 0xffff0000, v48
	v_lshlrev_b32_e32 v6, 16, v49
	v_and_b32_e32 v7, 0xffff0000, v49
	v_lshlrev_b32_e32 v22, 16, v44
	v_and_b32_e32 v23, 0xffff0000, v44
	v_lshlrev_b32_e32 v28, 16, v45
	v_and_b32_e32 v29, 0xffff0000, v45
	v_pk_add_f32 v[4:5], v[26:27], v[4:5]
	v_pk_add_f32 v[6:7], v[8:9], v[6:7]
	v_lshlrev_b32_e32 v44, 16, v61
	v_and_b32_e32 v45, 0xffff0000, v61
	v_fma_f32 v61, -v51, v60, 1.0
	v_pk_add_f32 v[4:5], v[4:5], v[22:23]
	v_pk_add_f32 v[6:7], v[6:7], v[28:29]
	v_fmac_f32_e32 v60, v61, v60
	v_div_scale_f32 v61, vcc, 1.0, v50, 1.0
	v_pk_add_f32 v[4:5], v[4:5], v[38:39]
	v_lshlrev_b32_e32 v22, 16, v16
	v_and_b32_e32 v23, 0xffff0000, v16
	v_pk_add_f32 v[6:7], v[6:7], v[44:45]
	v_lshlrev_b32_e32 v8, 16, v17
	v_and_b32_e32 v9, 0xffff0000, v17
	v_lshlrev_b32_e32 v30, 16, v46
	v_and_b32_e32 v31, 0xffff0000, v46
	v_lshlrev_b32_e32 v36, 16, v47
	v_and_b32_e32 v37, 0xffff0000, v47
	v_lshlrev_b32_e32 v46, 16, v62
	v_and_b32_e32 v47, 0xffff0000, v62
	v_mul_f32_e32 v62, v61, v60
	v_pk_add_f32 v[4:5], v[4:5], v[22:23]
	v_lshlrev_b32_e32 v22, 16, v40
	v_and_b32_e32 v23, 0xffff0000, v40
	v_pk_add_f32 v[6:7], v[6:7], v[8:9]
	v_lshlrev_b32_e32 v8, 16, v41
	v_and_b32_e32 v9, 0xffff0000, v41
	v_lshlrev_b32_e32 v48, 16, v63
	v_and_b32_e32 v49, 0xffff0000, v63
	v_fma_f32 v63, -v51, v62, v61
	v_pk_add_f32 v[4:5], v[4:5], v[22:23]
	v_lshlrev_b32_e32 v22, 16, v32
	v_and_b32_e32 v23, 0xffff0000, v32
	v_pk_add_f32 v[6:7], v[6:7], v[8:9]
	v_lshlrev_b32_e32 v8, 16, v33
	v_and_b32_e32 v9, 0xffff0000, v33
	v_fmac_f32_e32 v62, v63, v60
	v_pk_add_f32 v[4:5], v[4:5], v[22:23]
	v_lshlrev_b32_e32 v22, 16, v56
	v_and_b32_e32 v23, 0xffff0000, v56
	v_pk_add_f32 v[6:7], v[6:7], v[8:9]
	v_lshlrev_b32_e32 v8, 16, v57
	v_and_b32_e32 v9, 0xffff0000, v57
	v_fma_f32 v51, -v51, v62, v61
	v_pk_add_f32 v[4:5], v[4:5], v[22:23]
	v_lshlrev_b32_e32 v22, 16, v52
	v_and_b32_e32 v23, 0xffff0000, v52
	v_pk_add_f32 v[6:7], v[6:7], v[8:9]
	v_lshlrev_b32_e32 v8, 16, v53
	v_and_b32_e32 v9, 0xffff0000, v53
	v_div_fmas_f32 v51, v51, v60, v62
	v_pk_add_f32 v[4:5], v[4:5], v[22:23]
	v_lshlrev_b32_e32 v22, 16, v64
	v_and_b32_e32 v23, 0xffff0000, v64
	v_pk_add_f32 v[6:7], v[6:7], v[8:9]
	v_lshlrev_b32_e32 v8, 16, v65
	v_and_b32_e32 v9, 0xffff0000, v65
	v_div_fixup_f32 v50, v51, v50, 1.0
	v_pk_add_f32 v[4:5], v[4:5], v[22:23]
	v_pk_add_f32 v[6:7], v[6:7], v[8:9]
	v_pk_fma_f32 v[4:5], v[50:51], v[4:5], v[94:95] op_sel_hi:[0,1,1] neg_lo:[0,0,1] neg_hi:[0,0,1]
	v_pk_fma_f32 v[6:7], v[50:51], v[6:7], v[82:83] op_sel_hi:[0,1,1] neg_lo:[0,0,1] neg_hi:[0,0,1]
	v_cvt_pk_bf16_f32 v4, v4, v5
	v_cvt_pk_bf16_f32 v5, v6, v7
	v_pk_add_f32 v[6:7], v[12:13], v[14:15]
	v_lshlrev_b32_e32 v8, 16, v18
	v_pk_add_f32 v[6:7], v[6:7], v[30:31]
	v_and_b32_e32 v9, 0xffff0000, v18
	v_pk_add_f32 v[6:7], v[6:7], v[46:47]
	s_add_i32 s6, s6, s4
	v_pk_add_f32 v[6:7], v[6:7], v[8:9]
	v_lshlrev_b32_e32 v8, 16, v42
	v_and_b32_e32 v9, 0xffff0000, v42
	v_pk_add_f32 v[6:7], v[6:7], v[8:9]
	v_lshlrev_b32_e32 v8, 16, v34
	v_and_b32_e32 v9, 0xffff0000, v34
	v_pk_add_f32 v[6:7], v[6:7], v[8:9]
	v_lshlrev_b32_e32 v8, 16, v58
	v_and_b32_e32 v9, 0xffff0000, v58
	v_pk_add_f32 v[6:7], v[6:7], v[8:9]
	v_lshlrev_b32_e32 v8, 16, v54
	v_and_b32_e32 v9, 0xffff0000, v54
	v_pk_add_f32 v[6:7], v[6:7], v[8:9]
	v_lshlrev_b32_e32 v8, 16, v66
	v_and_b32_e32 v9, 0xffff0000, v66
	v_pk_add_f32 v[6:7], v[6:7], v[8:9]
	v_pk_add_f32 v[8:9], v[10:11], v[20:21]
	v_lshlrev_b32_e32 v10, 16, v19
	v_pk_add_f32 v[8:9], v[8:9], v[36:37]
	v_and_b32_e32 v11, 0xffff0000, v19
	v_pk_add_f32 v[8:9], v[8:9], v[48:49]
	v_pk_fma_f32 v[6:7], v[50:51], v[6:7], v[80:81] op_sel_hi:[0,1,1] neg_lo:[0,0,1] neg_hi:[0,0,1]
	v_pk_add_f32 v[8:9], v[8:9], v[10:11]
	v_lshlrev_b32_e32 v10, 16, v43
	v_and_b32_e32 v11, 0xffff0000, v43
	v_pk_add_f32 v[8:9], v[8:9], v[10:11]
	v_lshlrev_b32_e32 v10, 16, v35
	v_and_b32_e32 v11, 0xffff0000, v35
	v_pk_add_f32 v[8:9], v[8:9], v[10:11]
	v_lshlrev_b32_e32 v10, 16, v59
	v_and_b32_e32 v11, 0xffff0000, v59
	v_pk_add_f32 v[8:9], v[8:9], v[10:11]
	v_lshlrev_b32_e32 v10, 16, v55
	v_and_b32_e32 v11, 0xffff0000, v55
	v_pk_add_f32 v[8:9], v[8:9], v[10:11]
	v_lshlrev_b32_e32 v10, 16, v67
	v_and_b32_e32 v11, 0xffff0000, v67
	v_pk_add_f32 v[8:9], v[8:9], v[10:11]
	v_cvt_pk_bf16_f32 v6, v6, v7
	v_pk_fma_f32 v[8:9], v[50:51], v[8:9], v[24:25] op_sel_hi:[0,1,1] neg_lo:[0,0,1] neg_hi:[0,0,1]
	v_cvt_pk_bf16_f32 v7, v8, v9
	v_add_co_u32_e32 v8, vcc, s5, v78
	s_add_i32 s2, s6, 15
	s_nop 0
	v_addc_co_u32_e32 v9, vcc, 0, v79, vcc
	global_store_dwordx4 v[8:9], v[4:7], off
	s_cmp_lt_i32 s2, 0x8000
	v_lshl_add_u64 v[76:77], v[76:77], 0, s[14:15]
	v_lshl_add_u64 v[4:5], s[0:1], 0, v[74:75]
	v_add_co_u32_e32 v6, vcc, s16, v4
	v_lshl_add_u64 v[74:75], v[74:75], 0, s[12:13]
	s_nop 0
	v_addc_co_u32_e32 v7, vcc, 0, v5, vcc
	v_mov_b32_e32 v6, v102
	v_mov_b32_e32 v7, v103
	v_lshlrev_b32_e32 v106, 16, v104
	v_and_b32_e32 v107, 0xffff0000, v104
	v_and_b32_e32 v9, 0xffff0000, v7
	v_and_b32_e32 v11, 0xffff0000, v6
	v_lshlrev_b32_e32 v8, 16, v7
	v_lshlrev_b32_e32 v10, 16, v6
	v_mov_b32_e32 v12, v11
	v_mov_b32_e32 v13, v9
	v_mov_b32_e32 v6, v10
	v_mov_b32_e32 v7, v8
	v_pk_mul_f32 v[12:13], v[12:13], v[12:13]
	s_nop 0
	v_pk_fma_f32 v[6:7], v[6:7], v[6:7], v[12:13]
	s_nop 0
	v_add_f32_e32 v6, v6, v7
	v_pk_mul_f32 v[108:109], v[106:107], v[106:107]
	s_nop 0
	v_add_f32_e32 v108, v108, v109
	s_nop 0
	v_add_f32_dpp v6, v6, v6 quad_perm:[1,0,3,2] row_mask:0xf bank_mask:0xf
	v_add_f32_dpp v108, v108, v108 quad_perm:[1,0,3,2] row_mask:0xf bank_mask:0xf
	s_nop 0
	v_add_f32_dpp v6, v6, v6 quad_perm:[2,3,0,1] row_mask:0xf bank_mask:0xf
	v_add_f32_dpp v108, v108, v108 quad_perm:[2,3,0,1] row_mask:0xf bank_mask:0xf
	s_nop 0
	v_add_f32_dpp v6, v6, v6 row_half_mirror row_mask:0xf bank_mask:0xf
	v_add_f32_dpp v108, v108, v108 row_half_mirror row_mask:0xf bank_mask:0xf
	s_nop 0
	v_add_f32_dpp v6, v6, v6 row_mirror row_mask:0xf bank_mask:0xf
	v_add_f32_dpp v108, v108, v108 row_mirror row_mask:0xf bank_mask:0xf
	s_nop 0
	v_mov_b32_e32 v7, v6
	v_mov_b32_e32 v109, v108
	s_nop 1
	v_permlane16_swap_b32_e32 v6, v7
	v_permlane16_swap_b32_e32 v108, v109
	v_add_f32_e32 v6, v6, v7
	v_add_f32_e32 v108, v108, v109
	v_mov_b32_e32 v7, v6
	v_mov_b32_e32 v109, v108
	s_nop 1
	v_permlane32_swap_b32_e32 v6, v7
	v_permlane32_swap_b32_e32 v108, v109
	v_add_f32_e32 v6, v6, v7
	v_add_f32_e32 v108, v108, v109
	v_fmamk_f32 v6, v6, 0x3b800000, v91
	v_mul_f32_e32 v7, 0x4b800000, v6
	v_cmp_gt_f32_e32 vcc, s17, v6
	s_nop 1
	v_cndmask_b32_e32 v6, v6, v7, vcc
	v_rsq_f32_e32 v6, v6
	s_nop 0
	v_mul_f32_e32 v7, 0x45800000, v6
	v_cndmask_b32_e32 v6, v6, v7, vcc
	v_pk_mul_f32 v[10:11], v[6:7], v[10:11] op_sel_hi:[0,1]
	v_pk_mul_f32 v[6:7], v[6:7], v[8:9] op_sel_hi:[0,1]
	v_pk_mul_f32 v[10:11], v[0:1], v[10:11]
	v_pk_mul_f32 v[6:7], v[2:3], v[6:7]
	v_add_co_u32_e32 v4, vcc, s18, v4
	v_cvt_pk_bf16_f32 v10, v10, v11
	v_cvt_pk_bf16_f32 v11, v6, v7
	v_addc_co_u32_e32 v5, vcc, 0, v5, vcc
	global_store_dwordx2 v[4:5], v[10:11], off
	v_lshl_add_u64 v[4:5], s[0:1], 0, v[72:73]
	v_lshl_add_u64 v[72:73], v[72:73], 0, s[8:9]
	v_fmamk_f32 v108, v108, 0x3c000000, v91
	v_mul_f32_e32 v109, 0x4b800000, v108
	v_cmp_gt_f32_e32 vcc, s17, v108
	s_nop 1
	v_cndmask_b32_e32 v108, v108, v109, vcc
	v_rsq_f32_e32 v108, v108
	s_nop 0
	v_mul_f32_e32 v109, 0x45800000, v108
	v_cndmask_b32_e32 v108, v108, v109, vcc
	v_pk_mul_f32 v[6:7], v[108:109], v[106:107] op_sel_hi:[0,1]
	v_pk_mul_f32 v[6:7], v[68:69], v[6:7]
	v_add_co_u32_e32 v4, vcc, 0x13a00000, v4
	v_cvt_pk_bf16_f32 v6, v6, v7
	s_nop 0
	v_addc_co_u32_e32 v5, vcc, 0, v5, vcc
	global_store_dword v[4:5], v6, off
	s_cbranch_scc0 .LBB0_405

.LBB0_834:
	v_lshl_add_u32 v188, s52, 8, v199
	v_lshl_or_b32 v186, s50, 8, v201
	v_ashrrev_i32_e32 v187, 31, v186
	v_ashrrev_i32_e32 v189, 31, v188
	v_lshl_add_u64 v[190:191], v[186:187], 2, s[14:15]
	v_lshlrev_b64 v[128:129], 12, v[188:189]
	v_lshl_add_u64 v[128:129], v[190:191], 0, v[128:129]
	global_load_dwordx4 v[208:211], v[128:129], off
	global_load_dwordx4 v[212:215], v[128:129], off offset:16
	global_load_dwordx4 v[216:219], v[128:129], off offset:512
	global_load_dwordx4 v[220:223], v[128:129], off offset:528
	v_or_b32_e32 v196, 16, v188
	v_or_b32_e32 v194, 32, v188
	v_or_b32_e32 v192, 48, v188
	v_ashrrev_i32_e32 v197, 31, v196
	v_ashrrev_i32_e32 v195, 31, v194
	v_ashrrev_i32_e32 v193, 31, v192
	v_lshlrev_b64 v[128:129], 12, v[196:197]
	v_lshlrev_b64 v[130:131], 12, v[194:195]
	v_lshlrev_b64 v[132:133], 12, v[192:193]
	v_lshl_add_u64 v[128:129], v[190:191], 0, v[128:129]
	v_lshl_add_u64 v[130:131], v[190:191], 0, v[130:131]
	v_lshl_add_u64 v[132:133], v[190:191], 0, v[132:133]
	global_load_dwordx4 v[168:171], v[128:129], off offset:16
	global_load_dwordx4 v[172:175], v[128:129], off
	global_load_dwordx4 v[160:163], v[128:129], off offset:528
	global_load_dwordx4 v[164:167], v[128:129], off offset:512
	global_load_dwordx4 v[152:155], v[130:131], off offset:16
	global_load_dwordx4 v[156:159], v[130:131], off
	global_load_dwordx4 v[144:147], v[130:131], off offset:528
	global_load_dwordx4 v[148:151], v[130:131], off offset:512
	global_load_dwordx4 v[136:139], v[132:133], off offset:16
	global_load_dwordx4 v[140:143], v[132:133], off
	s_nop 0
	global_load_dwordx4 v[128:131], v[132:133], off offset:528
	s_nop 0
	global_load_dwordx4 v[132:135], v[132:133], off offset:512
	v_and_b32_e32 v207, 64, v205
	v_xor_b32_e32 v206, 16, v205
	v_add_u32_e32 v207, 64, v207
	v_xor_b32_e32 v224, 32, v205
	v_cmp_lt_i32_e32 vcc, v206, v207
	s_waitcnt vmcnt(0)
	v_pk_add_f32 v[126:127], v[126:127], v[210:211]
	v_cndmask_b32_e32 v206, v205, v206, vcc
	v_cmp_lt_i32_e32 vcc, v224, v207
	v_lshlrev_b32_e32 v207, 2, v206
	v_pk_add_f32 v[124:125], v[124:125], v[208:209]
	v_cndmask_b32_e32 v226, v205, v224, vcc
	v_lshlrev_b64 v[224:225], 10, v[188:189]
	v_lshl_add_u64 v[224:225], v[224:225], 0, v[186:187]
	v_lshlrev_b32_e32 v206, 2, v226
	v_lshl_add_u64 v[226:227], v[224:225], 2, s[16:17]
	v_pk_add_f32 v[118:119], v[118:119], v[218:219]
	v_pk_add_f32 v[116:117], v[116:117], v[216:217]
	v_pk_add_f32 v[122:123], v[122:123], v[214:215]
	v_pk_add_f32 v[120:121], v[120:121], v[212:213]
	v_pk_add_f32 v[208:209], v[112:113], v[220:221]
	global_store_dwordx4 v[226:227], v[124:127], off
	global_store_dwordx4 v[226:227], v[120:123], off offset:16
	v_cvt_pk_bf16_f32 v112, v124, v125
	v_cvt_pk_bf16_f32 v113, v126, v127
	v_mul_f32_e32 v125, v125, v125
	v_mul_f32_e32 v127, v127, v127
	v_mul_f32_e32 v212, v117, v117
	v_mul_f32_e32 v213, v119, v119
	v_pk_add_f32 v[210:211], v[114:115], v[222:223]
	v_cvt_pk_bf16_f32 v114, v120, v121
	v_cvt_pk_bf16_f32 v115, v122, v123
	v_mul_f32_e32 v121, v121, v121
	v_mul_f32_e32 v123, v123, v123
	v_mul_f32_e32 v214, v209, v209
	v_fmac_f32_e32 v125, v124, v124
	v_fmac_f32_e32 v127, v126, v126
	v_fmac_f32_e32 v212, v116, v116
	v_fmac_f32_e32 v213, v118, v118
	v_mul_f32_e32 v215, v211, v211
	v_fmac_f32_e32 v121, v120, v120
	v_fmac_f32_e32 v123, v122, v122
	v_fmac_f32_e32 v214, v208, v208
	v_add_f32_e32 v120, v125, v127
	v_add_f32_e32 v122, v212, v213
	v_fmac_f32_e32 v215, v210, v210
	v_add_f32_e32 v120, v120, v121
	v_add_f32_e32 v121, v122, v214
	v_add_f32_e32 v120, v123, v120
	v_add_f32_e32 v121, v215, v121
	v_add_f32_e32 v120, v120, v121
	v_mov_b32_e32 v121, v120
	s_nop 1
	v_permlane16_swap_b32_e32 v120, v121
	v_lshl_add_u64 v[224:225], v[224:225], 1, s[24:25]
	global_store_dwordx4 v[224:225], v[112:115], off
	global_store_dwordx4 v[226:227], v[116:119], off offset:512
	global_store_dwordx4 v[226:227], v[208:211], off offset:528
	v_cvt_pk_bf16_f32 v114, v116, v117
	v_cvt_pk_bf16_f32 v115, v118, v119
	s_waitcnt lgkmcnt(0)
	v_add_f32_e32 v112, v120, v121
	v_mov_b32_e32 v113, v112
	s_nop 1
	v_permlane32_swap_b32_e32 v112, v113
	v_cvt_pk_bf16_f32 v116, v208, v209
	v_cvt_pk_bf16_f32 v117, v210, v211
	global_store_dwordx4 v[224:225], v[114:117], off offset:256
	s_and_saveexec_b64 s[2:3], s[6:7]
	s_cbranch_execz .LBB0_836
	v_lshl_add_u64 v[114:115], v[188:189], 2, s[28:29]
	s_waitcnt lgkmcnt(0)
	v_add_f32_e32 v112, v112, v113
	global_atomic_add_f32 v[114:115], v112, off
.LBB0_836:
	s_or_b64 exec, exec, s[2:3]
	s_waitcnt lgkmcnt(0)
	v_lshlrev_b64 v[112:113], 10, v[196:197]
	v_lshl_add_u64 v[112:113], v[112:113], 0, v[186:187]
	v_pk_add_f32 v[110:111], v[110:111], v[174:175]
	v_pk_add_f32 v[108:109], v[108:109], v[172:173]
	v_lshl_add_u64 v[116:117], v[112:113], 2, s[16:17]
	v_pk_add_f32 v[106:107], v[106:107], v[170:171]
	v_pk_add_f32 v[104:105], v[104:105], v[168:169]
	global_store_dwordx4 v[116:117], v[108:111], off
	global_store_dwordx4 v[116:117], v[104:107], off offset:16
	v_lshl_add_u64 v[118:119], v[112:113], 1, s[24:25]
	v_cvt_pk_bf16_f32 v112, v108, v109
	v_mul_f32_e32 v109, v109, v109
	v_fmac_f32_e32 v109, v108, v108
	v_mul_f32_e32 v108, v111, v111
	v_cvt_pk_bf16_f32 v114, v104, v105
	v_fmac_f32_e32 v108, v110, v110
	v_mul_f32_e32 v105, v105, v105
	v_add_f32_e32 v108, v109, v108
	v_fmac_f32_e32 v105, v104, v104
	v_add_f32_e32 v104, v108, v105
	v_mul_f32_e32 v105, v107, v107
	v_fmac_f32_e32 v105, v106, v106
	v_pk_add_f32 v[102:103], v[102:103], v[166:167]
	v_pk_add_f32 v[100:101], v[100:101], v[164:165]
	v_add_f32_e32 v108, v105, v104
	v_pk_add_f32 v[104:105], v[96:97], v[160:161]
	v_mul_f32_e32 v96, v101, v101
	v_mul_f32_e32 v97, v103, v103
	v_fmac_f32_e32 v96, v100, v100
	v_fmac_f32_e32 v97, v102, v102
	v_add_f32_e32 v96, v96, v97
	v_mul_f32_e32 v97, v105, v105
	v_cvt_pk_bf16_f32 v115, v106, v107
	v_pk_add_f32 v[106:107], v[98:99], v[162:163]
	v_fmac_f32_e32 v97, v104, v104
	v_add_f32_e32 v96, v96, v97
	v_mul_f32_e32 v97, v107, v107
	v_fmac_f32_e32 v97, v106, v106
	v_add_f32_e32 v96, v97, v96
	v_add_f32_e32 v96, v108, v96
	v_mov_b32_e32 v97, v96
	s_nop 1
	v_permlane16_swap_b32_e32 v96, v97
	v_cvt_pk_bf16_f32 v113, v110, v111
	global_store_dwordx4 v[118:119], v[112:115], off
	global_store_dwordx4 v[116:117], v[100:103], off offset:512
	global_store_dwordx4 v[116:117], v[104:107], off offset:528
	v_cvt_pk_bf16_f32 v98, v100, v101
	v_cvt_pk_bf16_f32 v99, v102, v103
	s_waitcnt lgkmcnt(0)
	v_add_f32_e32 v96, v96, v97
	v_mov_b32_e32 v97, v96
	s_nop 1
	v_permlane32_swap_b32_e32 v96, v97
	v_cvt_pk_bf16_f32 v100, v104, v105
	v_cvt_pk_bf16_f32 v101, v106, v107
	global_store_dwordx4 v[118:119], v[98:101], off offset:256
	s_and_saveexec_b64 s[2:3], s[6:7]
	s_cbranch_execz .LBB0_838
	v_lshl_add_u64 v[98:99], v[196:197], 2, s[28:29]
	s_waitcnt lgkmcnt(0)
	v_add_f32_e32 v96, v96, v97
	global_atomic_add_f32 v[98:99], v96, off
.LBB0_838:
	s_or_b64 exec, exec, s[2:3]
	v_add_u32_e32 v162, 0x80, v188
	v_ashrrev_i32_e32 v163, 31, v162
	s_waitcnt lgkmcnt(0)
	v_lshlrev_b64 v[96:97], 12, v[162:163]
	v_add_u32_e32 v160, 0x90, v188
	v_lshl_add_u64 v[96:97], v[190:191], 0, v[96:97]
	v_ashrrev_i32_e32 v161, 31, v160
	global_load_dwordx4 v[120:123], v[96:97], off offset:16
	global_load_dwordx4 v[124:127], v[96:97], off
	global_load_dwordx4 v[112:115], v[96:97], off offset:528
	global_load_dwordx4 v[116:119], v[96:97], off offset:512
	v_lshlrev_b64 v[96:97], 12, v[160:161]
	v_lshl_add_u64 v[100:101], v[190:191], 0, v[96:97]
	global_load_dwordx4 v[104:107], v[100:101], off offset:16
	global_load_dwordx4 v[108:111], v[100:101], off
	global_load_dwordx4 v[96:99], v[100:101], off offset:528
	s_nop 0
	global_load_dwordx4 v[100:103], v[100:101], off offset:512
	v_lshlrev_b64 v[164:165], 10, v[194:195]
	v_lshl_add_u64 v[164:165], v[164:165], 0, v[186:187]
	v_pk_add_f32 v[94:95], v[94:95], v[158:159]
	v_pk_add_f32 v[92:93], v[92:93], v[156:157]
	v_lshl_add_u64 v[156:157], v[164:165], 2, s[16:17]
	v_pk_add_f32 v[90:91], v[90:91], v[154:155]
	v_pk_add_f32 v[88:89], v[88:89], v[152:153]
	global_store_dwordx4 v[156:157], v[92:95], off
	global_store_dwordx4 v[156:157], v[88:91], off offset:16
	v_cvt_pk_bf16_f32 v152, v92, v93
	v_mul_f32_e32 v93, v93, v93
	v_fmac_f32_e32 v93, v92, v92
	v_mul_f32_e32 v92, v95, v95
	v_cvt_pk_bf16_f32 v154, v88, v89
	v_fmac_f32_e32 v92, v94, v94
	v_mul_f32_e32 v89, v89, v89
	v_add_f32_e32 v92, v93, v92
	v_fmac_f32_e32 v89, v88, v88
	v_add_f32_e32 v88, v92, v89
	v_mul_f32_e32 v89, v91, v91
	v_fmac_f32_e32 v89, v90, v90
	v_pk_add_f32 v[86:87], v[86:87], v[150:151]
	v_pk_add_f32 v[84:85], v[84:85], v[148:149]
	v_add_f32_e32 v92, v89, v88
	v_pk_add_f32 v[88:89], v[80:81], v[144:145]
	v_mul_f32_e32 v80, v85, v85
	v_mul_f32_e32 v81, v87, v87
	v_fmac_f32_e32 v80, v84, v84
	v_fmac_f32_e32 v81, v86, v86
	v_add_f32_e32 v80, v80, v81
	v_mul_f32_e32 v81, v89, v89
	v_cvt_pk_bf16_f32 v155, v90, v91
	v_pk_add_f32 v[90:91], v[82:83], v[146:147]
	v_fmac_f32_e32 v81, v88, v88
	v_add_f32_e32 v80, v80, v81
	v_mul_f32_e32 v81, v91, v91
	v_fmac_f32_e32 v81, v90, v90
	v_add_f32_e32 v80, v81, v80
	v_add_f32_e32 v80, v92, v80
	v_mov_b32_e32 v81, v80
	s_nop 1
	v_permlane16_swap_b32_e32 v80, v81
	v_lshl_add_u64 v[158:159], v[164:165], 1, s[24:25]
	v_cvt_pk_bf16_f32 v153, v94, v95
	global_store_dwordx4 v[158:159], v[152:155], off
	global_store_dwordx4 v[156:157], v[84:87], off offset:512
	global_store_dwordx4 v[156:157], v[88:91], off offset:528
	v_cvt_pk_bf16_f32 v82, v84, v85
	s_waitcnt lgkmcnt(0)
	v_add_f32_e32 v80, v80, v81
	v_mov_b32_e32 v81, v80
	s_nop 1
	v_permlane32_swap_b32_e32 v80, v81
	v_cvt_pk_bf16_f32 v83, v86, v87
	v_cvt_pk_bf16_f32 v84, v88, v89
	v_cvt_pk_bf16_f32 v85, v90, v91
	global_store_dwordx4 v[158:159], v[82:85], off offset:256
	s_and_saveexec_b64 s[2:3], s[6:7]
	v_readlane_b32 s72, v254, 21
	v_readlane_b32 s73, v254, 22
	s_cbranch_execz .LBB0_840
	v_lshl_add_u64 v[82:83], v[194:195], 2, s[28:29]
	s_waitcnt lgkmcnt(0)
	v_add_f32_e32 v80, v80, v81
	global_atomic_add_f32 v[82:83], v80, off
.LBB0_840:
	s_or_b64 exec, exec, s[2:3]
	s_waitcnt lgkmcnt(0)
	v_lshlrev_b64 v[80:81], 10, v[192:193]
	v_lshl_add_u64 v[80:81], v[80:81], 0, v[186:187]
	v_pk_add_f32 v[78:79], v[78:79], v[142:143]
	v_pk_add_f32 v[76:77], v[76:77], v[140:141]
	v_lshl_add_u64 v[84:85], v[80:81], 2, s[16:17]
	v_pk_add_f32 v[74:75], v[74:75], v[138:139]
	v_pk_add_f32 v[72:73], v[72:73], v[136:137]
	global_store_dwordx4 v[84:85], v[76:79], off
	global_store_dwordx4 v[84:85], v[72:75], off offset:16
	v_lshl_add_u64 v[86:87], v[80:81], 1, s[24:25]
	v_cvt_pk_bf16_f32 v80, v76, v77
	v_mul_f32_e32 v77, v77, v77
	v_fmac_f32_e32 v77, v76, v76
	v_mul_f32_e32 v76, v79, v79
	v_cvt_pk_bf16_f32 v82, v72, v73
	v_fmac_f32_e32 v76, v78, v78
	v_mul_f32_e32 v73, v73, v73
	v_add_f32_e32 v76, v77, v76
	v_fmac_f32_e32 v73, v72, v72
	v_add_f32_e32 v72, v76, v73
	v_mul_f32_e32 v73, v75, v75
	v_fmac_f32_e32 v73, v74, v74
	v_pk_add_f32 v[70:71], v[70:71], v[134:135]
	v_pk_add_f32 v[68:69], v[68:69], v[132:133]
	v_add_f32_e32 v76, v73, v72
	v_pk_add_f32 v[72:73], v[64:65], v[128:129]
	v_mul_f32_e32 v64, v69, v69
	v_mul_f32_e32 v65, v71, v71
	v_fmac_f32_e32 v64, v68, v68
	v_fmac_f32_e32 v65, v70, v70
	v_add_f32_e32 v64, v64, v65
	v_mul_f32_e32 v65, v73, v73
	v_cvt_pk_bf16_f32 v83, v74, v75
	v_pk_add_f32 v[74:75], v[66:67], v[130:131]
	v_fmac_f32_e32 v65, v72, v72
	v_add_f32_e32 v64, v64, v65
	v_mul_f32_e32 v65, v75, v75
	v_fmac_f32_e32 v65, v74, v74
	v_add_f32_e32 v64, v65, v64
	v_add_f32_e32 v64, v76, v64
	v_mov_b32_e32 v65, v64
	s_nop 1
	v_permlane16_swap_b32_e32 v64, v65
	v_cvt_pk_bf16_f32 v81, v78, v79
	global_store_dwordx4 v[86:87], v[80:83], off
	global_store_dwordx4 v[84:85], v[68:71], off offset:512
	global_store_dwordx4 v[84:85], v[72:75], off offset:528
	v_cvt_pk_bf16_f32 v66, v68, v69
	v_cvt_pk_bf16_f32 v67, v70, v71
	s_waitcnt lgkmcnt(0)
	v_add_f32_e32 v64, v64, v65
	v_mov_b32_e32 v65, v64
	s_nop 1
	v_permlane32_swap_b32_e32 v64, v65
	v_cvt_pk_bf16_f32 v68, v72, v73
	v_cvt_pk_bf16_f32 v69, v74, v75
	global_store_dwordx4 v[86:87], v[66:69], off offset:256
	s_and_saveexec_b64 s[2:3], s[6:7]
	s_cbranch_execz .LBB0_842
	v_lshl_add_u64 v[66:67], v[192:193], 2, s[28:29]
	s_waitcnt lgkmcnt(0)
	v_add_f32_e32 v64, v64, v65
	global_atomic_add_f32 v[66:67], v64, off
.LBB0_842:
	s_or_b64 exec, exec, s[2:3]
	v_or_b32_e32 v64, 32, v162
	s_waitcnt lgkmcnt(0)
	v_ashrrev_i32_e32 v65, 31, v64
	v_lshlrev_b64 v[64:65], 12, v[64:65]
	v_add_u32_e32 v128, 0xb0, v188
	v_lshl_add_u64 v[64:65], v[190:191], 0, v[64:65]
	v_ashrrev_i32_e32 v129, 31, v128
	global_load_dwordx4 v[88:91], v[64:65], off offset:16
	global_load_dwordx4 v[92:95], v[64:65], off
	global_load_dwordx4 v[80:83], v[64:65], off offset:528
	global_load_dwordx4 v[84:87], v[64:65], off offset:512
	v_lshlrev_b64 v[64:65], 12, v[128:129]
	v_lshl_add_u64 v[68:69], v[190:191], 0, v[64:65]
	global_load_dwordx4 v[72:75], v[68:69], off offset:16
	global_load_dwordx4 v[76:79], v[68:69], off
	global_load_dwordx4 v[64:67], v[68:69], off offset:528
	s_nop 0
	global_load_dwordx4 v[68:71], v[68:69], off offset:512
	v_lshlrev_b64 v[130:131], 10, v[162:163]
	v_lshl_add_u64 v[130:131], v[130:131], 0, v[186:187]
	s_waitcnt vmcnt(26)
	v_pk_add_f32 v[62:63], v[62:63], v[126:127]
	v_pk_add_f32 v[60:61], v[60:61], v[124:125]
	v_lshl_add_u64 v[124:125], v[130:131], 2, s[16:17]
	v_pk_add_f32 v[58:59], v[58:59], v[122:123]
	v_pk_add_f32 v[56:57], v[56:57], v[120:121]
	global_store_dwordx4 v[124:125], v[60:63], off
	global_store_dwordx4 v[124:125], v[56:59], off offset:16
	v_cvt_pk_bf16_f32 v120, v60, v61
	v_mul_f32_e32 v61, v61, v61
	v_fmac_f32_e32 v61, v60, v60
	v_mul_f32_e32 v60, v63, v63
	v_cvt_pk_bf16_f32 v122, v56, v57
	v_fmac_f32_e32 v60, v62, v62
	v_mul_f32_e32 v57, v57, v57
	v_add_f32_e32 v60, v61, v60
	v_fmac_f32_e32 v57, v56, v56
	v_add_f32_e32 v56, v60, v57
	v_mul_f32_e32 v57, v59, v59
	v_fmac_f32_e32 v57, v58, v58
	s_waitcnt vmcnt(26)
	v_pk_add_f32 v[54:55], v[54:55], v[118:119]
	v_pk_add_f32 v[52:53], v[52:53], v[116:117]
	v_add_f32_e32 v60, v57, v56
	v_pk_add_f32 v[56:57], v[48:49], v[112:113]
	v_mul_f32_e32 v48, v53, v53
	v_mul_f32_e32 v49, v55, v55
	v_fmac_f32_e32 v48, v52, v52
	v_fmac_f32_e32 v49, v54, v54
	v_add_f32_e32 v48, v48, v49
	v_mul_f32_e32 v49, v57, v57
	v_cvt_pk_bf16_f32 v123, v58, v59
	v_pk_add_f32 v[58:59], v[50:51], v[114:115]
	v_fmac_f32_e32 v49, v56, v56
	v_add_f32_e32 v48, v48, v49
	v_mul_f32_e32 v49, v59, v59
	v_fmac_f32_e32 v49, v58, v58
	v_add_f32_e32 v48, v49, v48
	v_add_f32_e32 v48, v60, v48
	v_mov_b32_e32 v49, v48
	s_nop 1
	v_permlane16_swap_b32_e32 v48, v49
	v_lshl_add_u64 v[126:127], v[130:131], 1, s[24:25]
	v_cvt_pk_bf16_f32 v121, v62, v63
	global_store_dwordx4 v[126:127], v[120:123], off
	global_store_dwordx4 v[124:125], v[52:55], off offset:512
	global_store_dwordx4 v[124:125], v[56:59], off offset:528
	v_cvt_pk_bf16_f32 v50, v52, v53
	s_waitcnt lgkmcnt(0)
	v_add_f32_e32 v48, v48, v49
	v_mov_b32_e32 v49, v48
	s_nop 1
	v_permlane32_swap_b32_e32 v48, v49
	v_cvt_pk_bf16_f32 v51, v54, v55
	v_cvt_pk_bf16_f32 v52, v56, v57
	v_cvt_pk_bf16_f32 v53, v58, v59
	global_store_dwordx4 v[126:127], v[50:53], off offset:256
	s_and_saveexec_b64 s[2:3], s[6:7]
	s_cbranch_execz .LBB0_844
	v_lshl_add_u64 v[50:51], v[162:163], 2, s[28:29]
	s_waitcnt lgkmcnt(0)
	v_add_f32_e32 v48, v48, v49
	global_atomic_add_f32 v[50:51], v48, off
.LBB0_844:
	s_or_b64 exec, exec, s[2:3]
	s_waitcnt lgkmcnt(0)
	v_lshlrev_b64 v[48:49], 10, v[160:161]
	v_lshl_add_u64 v[48:49], v[48:49], 0, v[186:187]
	s_waitcnt vmcnt(28)
	v_pk_add_f32 v[46:47], v[46:47], v[110:111]
	v_pk_add_f32 v[44:45], v[44:45], v[108:109]
	v_lshl_add_u64 v[52:53], v[48:49], 2, s[16:17]
	v_pk_add_f32 v[42:43], v[42:43], v[106:107]
	v_pk_add_f32 v[40:41], v[40:41], v[104:105]
	global_store_dwordx4 v[52:53], v[44:47], off
	global_store_dwordx4 v[52:53], v[40:43], off offset:16
	v_lshl_add_u64 v[54:55], v[48:49], 1, s[24:25]
	v_cvt_pk_bf16_f32 v48, v44, v45
	v_mul_f32_e32 v45, v45, v45
	v_fmac_f32_e32 v45, v44, v44
	v_mul_f32_e32 v44, v47, v47
	v_cvt_pk_bf16_f32 v50, v40, v41
	v_fmac_f32_e32 v44, v46, v46
	v_mul_f32_e32 v41, v41, v41
	v_add_f32_e32 v44, v45, v44
	v_fmac_f32_e32 v41, v40, v40
	v_add_f32_e32 v40, v44, v41
	v_mul_f32_e32 v41, v43, v43
	v_fmac_f32_e32 v41, v42, v42
	s_waitcnt vmcnt(28)
	v_pk_add_f32 v[38:39], v[38:39], v[102:103]
	v_pk_add_f32 v[36:37], v[36:37], v[100:101]
	v_add_f32_e32 v44, v41, v40
	v_pk_add_f32 v[40:41], v[32:33], v[96:97]
	v_mul_f32_e32 v32, v37, v37
	v_mul_f32_e32 v33, v39, v39
	v_fmac_f32_e32 v32, v36, v36
	v_fmac_f32_e32 v33, v38, v38
	v_add_f32_e32 v32, v32, v33
	v_mul_f32_e32 v33, v41, v41
	v_cvt_pk_bf16_f32 v51, v42, v43
	v_pk_add_f32 v[42:43], v[34:35], v[98:99]
	v_fmac_f32_e32 v33, v40, v40
	v_add_f32_e32 v32, v32, v33
	v_mul_f32_e32 v33, v43, v43
	v_fmac_f32_e32 v33, v42, v42
	v_add_f32_e32 v32, v33, v32
	v_add_f32_e32 v32, v44, v32
	v_mov_b32_e32 v33, v32
	s_nop 1
	v_permlane16_swap_b32_e32 v32, v33
	v_cvt_pk_bf16_f32 v49, v46, v47
	global_store_dwordx4 v[54:55], v[48:51], off
	global_store_dwordx4 v[52:53], v[36:39], off offset:512
	global_store_dwordx4 v[52:53], v[40:43], off offset:528
	v_cvt_pk_bf16_f32 v34, v36, v37
	v_cvt_pk_bf16_f32 v35, v38, v39
	s_waitcnt lgkmcnt(0)
	v_add_f32_e32 v32, v32, v33
	v_mov_b32_e32 v33, v32
	s_nop 1
	v_permlane32_swap_b32_e32 v32, v33
	v_cvt_pk_bf16_f32 v36, v40, v41
	v_cvt_pk_bf16_f32 v37, v42, v43
	global_store_dwordx4 v[54:55], v[34:37], off offset:256
	s_and_saveexec_b64 s[2:3], s[6:7]
	s_cbranch_execz .LBB0_846
	v_lshl_add_u64 v[34:35], v[160:161], 2, s[28:29]
	s_waitcnt lgkmcnt(0)
	v_add_f32_e32 v32, v32, v33
	global_atomic_add_f32 v[34:35], v32, off
.LBB0_846:
	s_or_b64 exec, exec, s[2:3]
	v_add_u32_e32 v32, 0xa0, v188
	s_waitcnt lgkmcnt(0)
	v_ashrrev_i32_e32 v33, 31, v32
	v_lshlrev_b64 v[34:35], 10, v[32:33]
	v_lshl_add_u64 v[34:35], v[34:35], 0, v[186:187]
	s_waitcnt vmcnt(18)
	v_pk_add_f32 v[30:31], v[30:31], v[94:95]
	v_pk_add_f32 v[28:29], v[28:29], v[92:93]
	v_lshl_add_u64 v[38:39], v[34:35], 2, s[16:17]
	v_pk_add_f32 v[26:27], v[26:27], v[90:91]
	v_pk_add_f32 v[24:25], v[24:25], v[88:89]
	global_store_dwordx4 v[38:39], v[28:31], off
	global_store_dwordx4 v[38:39], v[24:27], off offset:16
	v_lshl_add_u64 v[40:41], v[34:35], 1, s[24:25]
	v_cvt_pk_bf16_f32 v34, v28, v29
	v_mul_f32_e32 v29, v29, v29
	v_fmac_f32_e32 v29, v28, v28
	v_mul_f32_e32 v28, v31, v31
	v_cvt_pk_bf16_f32 v36, v24, v25
	v_fmac_f32_e32 v28, v30, v30
	v_mul_f32_e32 v25, v25, v25
	v_add_f32_e32 v28, v29, v28
	v_fmac_f32_e32 v25, v24, v24
	v_add_f32_e32 v24, v28, v25
	v_mul_f32_e32 v25, v27, v27
	v_fmac_f32_e32 v25, v26, v26
	s_waitcnt vmcnt(18)
	v_pk_add_f32 v[22:23], v[22:23], v[86:87]
	v_pk_add_f32 v[20:21], v[20:21], v[84:85]
	v_add_f32_e32 v28, v25, v24
	v_pk_add_f32 v[24:25], v[16:17], v[80:81]
	v_mul_f32_e32 v16, v21, v21
	v_mul_f32_e32 v17, v23, v23
	v_fmac_f32_e32 v16, v20, v20
	v_fmac_f32_e32 v17, v22, v22
	v_add_f32_e32 v16, v16, v17
	v_mul_f32_e32 v17, v25, v25
	v_cvt_pk_bf16_f32 v37, v26, v27
	v_pk_add_f32 v[26:27], v[18:19], v[82:83]
	v_fmac_f32_e32 v17, v24, v24
	v_add_f32_e32 v16, v16, v17
	v_mul_f32_e32 v17, v27, v27
	v_fmac_f32_e32 v17, v26, v26
	v_add_f32_e32 v16, v17, v16
	v_add_f32_e32 v16, v28, v16
	v_mov_b32_e32 v17, v16
	s_nop 1
	v_permlane16_swap_b32_e32 v16, v17
	v_cvt_pk_bf16_f32 v35, v30, v31
	global_store_dwordx4 v[40:41], v[34:37], off
	global_store_dwordx4 v[38:39], v[20:23], off offset:512
	global_store_dwordx4 v[38:39], v[24:27], off offset:528
	v_cvt_pk_bf16_f32 v18, v20, v21
	v_cvt_pk_bf16_f32 v19, v22, v23
	s_waitcnt lgkmcnt(0)
	v_add_f32_e32 v16, v16, v17
	v_mov_b32_e32 v17, v16
	s_nop 1
	v_permlane32_swap_b32_e32 v16, v17
	v_cvt_pk_bf16_f32 v20, v24, v25
	v_cvt_pk_bf16_f32 v21, v26, v27
	global_store_dwordx4 v[40:41], v[18:21], off offset:256
	s_and_saveexec_b64 s[2:3], s[6:7]
	s_cbranch_execz .LBB0_848
	v_lshl_add_u64 v[18:19], v[32:33], 2, s[28:29]
	s_waitcnt lgkmcnt(0)
	v_add_f32_e32 v16, v16, v17
	global_atomic_add_f32 v[18:19], v16, off
.LBB0_848:
	s_or_b64 exec, exec, s[2:3]
	s_waitcnt lgkmcnt(0)
	v_lshlrev_b64 v[16:17], 10, v[128:129]
	v_lshl_add_u64 v[16:17], v[16:17], 0, v[186:187]
	s_waitcnt vmcnt(20)
	v_pk_add_f32 v[14:15], v[14:15], v[78:79]
	v_pk_add_f32 v[12:13], v[12:13], v[76:77]
	v_lshl_add_u64 v[20:21], v[16:17], 2, s[16:17]
	v_pk_add_f32 v[10:11], v[10:11], v[74:75]
	v_pk_add_f32 v[8:9], v[8:9], v[72:73]
	global_store_dwordx4 v[20:21], v[12:15], off
	global_store_dwordx4 v[20:21], v[8:11], off offset:16
	v_lshl_add_u64 v[22:23], v[16:17], 1, s[24:25]
	v_cvt_pk_bf16_f32 v16, v12, v13
	v_mul_f32_e32 v13, v13, v13
	v_fmac_f32_e32 v13, v12, v12
	v_mul_f32_e32 v12, v15, v15
	v_cvt_pk_bf16_f32 v18, v8, v9
	v_fmac_f32_e32 v12, v14, v14
	v_mul_f32_e32 v9, v9, v9
	v_add_f32_e32 v12, v13, v12
	v_fmac_f32_e32 v9, v8, v8
	v_add_f32_e32 v8, v12, v9
	v_mul_f32_e32 v9, v11, v11
	v_fmac_f32_e32 v9, v10, v10
	s_waitcnt vmcnt(20)
	v_pk_add_f32 v[6:7], v[6:7], v[70:71]
	v_pk_add_f32 v[4:5], v[4:5], v[68:69]
	v_add_f32_e32 v12, v9, v8
	v_pk_add_f32 v[8:9], v[0:1], v[64:65]
	v_mul_f32_e32 v0, v5, v5
	v_mul_f32_e32 v1, v7, v7
	v_fmac_f32_e32 v0, v4, v4
	v_fmac_f32_e32 v1, v6, v6
	v_add_f32_e32 v0, v0, v1
	v_mul_f32_e32 v1, v9, v9
	v_cvt_pk_bf16_f32 v19, v10, v11
	v_pk_add_f32 v[10:11], v[2:3], v[66:67]
	v_fmac_f32_e32 v1, v8, v8
	v_add_f32_e32 v0, v0, v1
	v_mul_f32_e32 v1, v11, v11
	v_fmac_f32_e32 v1, v10, v10
	v_add_f32_e32 v0, v1, v0
	v_add_f32_e32 v0, v12, v0
	v_mov_b32_e32 v1, v0
	s_nop 1
	v_permlane16_swap_b32_e32 v0, v1
	v_cvt_pk_bf16_f32 v17, v14, v15
	global_store_dwordx4 v[22:23], v[16:19], off
	global_store_dwordx4 v[20:21], v[4:7], off offset:512
	global_store_dwordx4 v[20:21], v[8:11], off offset:528
	v_cvt_pk_bf16_f32 v2, v4, v5
	v_cvt_pk_bf16_f32 v3, v6, v7
	s_waitcnt lgkmcnt(0)
	v_add_f32_e32 v0, v0, v1
	v_mov_b32_e32 v1, v0
	s_nop 1
	v_permlane32_swap_b32_e32 v0, v1
	v_cvt_pk_bf16_f32 v4, v8, v9
	v_cvt_pk_bf16_f32 v5, v10, v11
	global_store_dwordx4 v[22:23], v[2:5], off offset:256
	s_and_saveexec_b64 s[2:3], s[6:7]
	s_cbranch_execz .LBB0_850
	v_lshl_add_u64 v[2:3], v[128:129], 2, s[28:29]
	s_waitcnt lgkmcnt(0)
	v_add_f32_e32 v0, v0, v1
	global_atomic_add_f32 v[2:3], v0, off

.LBB0_1600:
	v_lshl_add_u32 v200, s0, 8, v193
	v_lshl_or_b32 v180, s33, 8, v215
	v_ashrrev_i32_e32 v181, 31, v180
	v_ashrrev_i32_e32 v201, 31, v200
	v_lshl_add_u64 v[182:183], v[180:181], 2, s[16:17]
	v_lshlrev_b64 v[128:129], 12, v[200:201]
	v_lshl_add_u64 v[224:225], v[182:183], 0, v[128:129]
	global_load_dwordx4 v[220:223], v[224:225], off
	global_load_dwordx4 v[234:237], v[224:225], off offset:16
	global_load_dwordx4 v[238:241], v[224:225], off offset:512
	global_load_dwordx4 v[242:245], v[224:225], off offset:528
	v_or_b32_e32 v210, 16, v200
	v_or_b32_e32 v206, 32, v200
	v_or_b32_e32 v202, 48, v200
	v_ashrrev_i32_e32 v211, 31, v210
	v_ashrrev_i32_e32 v207, 31, v206
	v_ashrrev_i32_e32 v203, 31, v202
	v_lshlrev_b64 v[128:129], 12, v[210:211]
	v_lshlrev_b64 v[130:131], 12, v[206:207]
	v_lshlrev_b64 v[132:133], 12, v[202:203]
	v_lshl_add_u64 v[212:213], v[182:183], 0, v[128:129]
	v_lshl_add_u64 v[208:209], v[182:183], 0, v[130:131]
	v_lshl_add_u64 v[204:205], v[182:183], 0, v[132:133]
	global_load_dwordx4 v[168:171], v[212:213], off offset:16
	global_load_dwordx4 v[172:175], v[212:213], off
	global_load_dwordx4 v[160:163], v[212:213], off offset:528
	global_load_dwordx4 v[164:167], v[212:213], off offset:512
	global_load_dwordx4 v[152:155], v[208:209], off offset:16
	global_load_dwordx4 v[156:159], v[208:209], off
	global_load_dwordx4 v[144:147], v[208:209], off offset:528
	global_load_dwordx4 v[148:151], v[208:209], off offset:512
	global_load_dwordx4 v[136:139], v[204:205], off offset:16
	global_load_dwordx4 v[140:143], v[204:205], off
	global_load_dwordx4 v[128:131], v[204:205], off offset:528
	global_load_dwordx4 v[132:135], v[204:205], off offset:512
	v_and_b32_e32 v218, 64, v233
	v_xor_b32_e32 v217, 16, v233
	v_add_u32_e32 v218, 64, v218
	v_xor_b32_e32 v219, 32, v233
	v_cmp_lt_i32_e32 vcc, v217, v218
	v_lshlrev_b64 v[246:247], 10, v[200:201]
	v_lshl_add_u64 v[246:247], v[246:247], 0, v[180:181]
	v_cndmask_b32_e32 v217, v233, v217, vcc
	v_cmp_lt_i32_e32 vcc, v219, v218
	v_lshlrev_b32_e32 v218, 2, v217
	v_lshl_add_u64 v[246:247], v[246:247], 1, s[10:11]
	v_cndmask_b32_e32 v219, v233, v219, vcc
	v_lshlrev_b32_e32 v217, 2, v219
	s_waitcnt vmcnt(0)
	v_pk_add_f32 v[126:127], v[126:127], v[222:223]
	v_pk_add_f32 v[124:125], v[124:125], v[220:221]
	v_pk_add_f32 v[118:119], v[118:119], v[240:241]
	v_pk_add_f32 v[116:117], v[116:117], v[238:239]
	v_pk_add_f32 v[122:123], v[122:123], v[236:237]
	v_pk_add_f32 v[120:121], v[120:121], v[234:235]
	v_pk_add_f32 v[220:221], v[112:113], v[242:243]
	global_store_dwordx4 v[224:225], v[124:127], off
	global_store_dwordx4 v[224:225], v[120:123], off offset:16
	v_cvt_pk_bf16_f32 v112, v124, v125
	v_cvt_pk_bf16_f32 v113, v126, v127
	v_mul_f32_e32 v125, v125, v125
	v_mul_f32_e32 v127, v127, v127
	v_mul_f32_e32 v219, v117, v117
	v_mul_f32_e32 v234, v119, v119
	v_pk_add_f32 v[222:223], v[114:115], v[244:245]
	v_cvt_pk_bf16_f32 v114, v120, v121
	v_cvt_pk_bf16_f32 v115, v122, v123
	v_mul_f32_e32 v121, v121, v121
	v_mul_f32_e32 v123, v123, v123
	v_mul_f32_e32 v235, v221, v221
	v_fmac_f32_e32 v125, v124, v124
	v_fmac_f32_e32 v127, v126, v126
	v_fmac_f32_e32 v219, v116, v116
	v_fmac_f32_e32 v234, v118, v118
	v_mul_f32_e32 v236, v223, v223
	v_fmac_f32_e32 v121, v120, v120
	v_fmac_f32_e32 v123, v122, v122
	v_fmac_f32_e32 v235, v220, v220
	v_add_f32_e32 v120, v125, v127
	v_add_f32_e32 v122, v219, v234
	v_fmac_f32_e32 v236, v222, v222
	v_add_f32_e32 v120, v120, v121
	v_add_f32_e32 v121, v122, v235
	v_add_f32_e32 v120, v123, v120
	v_add_f32_e32 v121, v236, v121
	v_add_f32_e32 v120, v120, v121
	v_mov_b32_e32 v121, v120
	s_nop 1
	v_permlane16_swap_b32_e32 v120, v121
	global_store_dwordx4 v[246:247], v[112:115], off
	global_store_dwordx4 v[224:225], v[116:119], off offset:512
	global_store_dwordx4 v[224:225], v[220:223], off offset:528
	v_cvt_pk_bf16_f32 v114, v116, v117
	v_cvt_pk_bf16_f32 v115, v118, v119
	v_cvt_pk_bf16_f32 v116, v220, v221
	s_waitcnt lgkmcnt(0)
	v_add_f32_e32 v112, v120, v121
	v_mov_b32_e32 v113, v112
	s_nop 1
	v_permlane32_swap_b32_e32 v112, v113
	v_cvt_pk_bf16_f32 v117, v222, v223
	global_store_dwordx4 v[246:247], v[114:117], off offset:256
	s_and_saveexec_b64 s[2:3], s[6:7]
	s_cbranch_execz .LBB0_1602
	v_lshl_add_u64 v[114:115], v[200:201], 2, s[12:13]
	s_waitcnt lgkmcnt(0)
	v_add_f32_e32 v112, v112, v113
	global_atomic_add_f32 v[114:115], v112, off
.LBB0_1602:
	s_or_b64 exec, exec, s[2:3]
	s_waitcnt lgkmcnt(0)
	v_lshlrev_b64 v[112:113], 10, v[210:211]
	v_lshl_add_u64 v[112:113], v[112:113], 0, v[180:181]
	v_pk_add_f32 v[110:111], v[110:111], v[174:175]
	v_pk_add_f32 v[108:109], v[108:109], v[172:173]
	v_pk_add_f32 v[106:107], v[106:107], v[170:171]
	v_pk_add_f32 v[104:105], v[104:105], v[168:169]
	global_store_dwordx4 v[212:213], v[108:111], off
	global_store_dwordx4 v[212:213], v[104:107], off offset:16
	v_lshl_add_u64 v[116:117], v[112:113], 1, s[10:11]
	v_cvt_pk_bf16_f32 v112, v108, v109
	v_mul_f32_e32 v109, v109, v109
	v_fmac_f32_e32 v109, v108, v108
	v_mul_f32_e32 v108, v111, v111
	v_cvt_pk_bf16_f32 v114, v104, v105
	v_fmac_f32_e32 v108, v110, v110
	v_mul_f32_e32 v105, v105, v105
	v_add_f32_e32 v108, v109, v108
	v_fmac_f32_e32 v105, v104, v104
	v_add_f32_e32 v104, v108, v105
	v_mul_f32_e32 v105, v107, v107
	v_fmac_f32_e32 v105, v106, v106
	v_pk_add_f32 v[102:103], v[102:103], v[166:167]
	v_pk_add_f32 v[100:101], v[100:101], v[164:165]
	v_add_f32_e32 v108, v105, v104
	v_pk_add_f32 v[104:105], v[96:97], v[160:161]
	v_mul_f32_e32 v96, v101, v101
	v_mul_f32_e32 v97, v103, v103
	v_fmac_f32_e32 v96, v100, v100
	v_fmac_f32_e32 v97, v102, v102
	v_add_f32_e32 v96, v96, v97
	v_mul_f32_e32 v97, v105, v105
	v_cvt_pk_bf16_f32 v115, v106, v107
	v_pk_add_f32 v[106:107], v[98:99], v[162:163]
	v_fmac_f32_e32 v97, v104, v104
	v_add_f32_e32 v96, v96, v97
	v_mul_f32_e32 v97, v107, v107
	v_fmac_f32_e32 v97, v106, v106
	v_add_f32_e32 v96, v97, v96
	v_add_f32_e32 v96, v108, v96
	v_mov_b32_e32 v97, v96
	s_nop 1
	v_permlane16_swap_b32_e32 v96, v97
	v_cvt_pk_bf16_f32 v113, v110, v111
	global_store_dwordx4 v[116:117], v[112:115], off
	global_store_dwordx4 v[212:213], v[100:103], off offset:512
	global_store_dwordx4 v[212:213], v[104:107], off offset:528
	v_cvt_pk_bf16_f32 v98, v100, v101
	v_cvt_pk_bf16_f32 v99, v102, v103
	s_waitcnt lgkmcnt(0)
	v_add_f32_e32 v96, v96, v97
	v_mov_b32_e32 v97, v96
	s_nop 1
	v_permlane32_swap_b32_e32 v96, v97
	v_cvt_pk_bf16_f32 v100, v104, v105
	v_cvt_pk_bf16_f32 v101, v106, v107
	global_store_dwordx4 v[116:117], v[98:101], off offset:256
	s_and_saveexec_b64 s[2:3], s[6:7]
	s_cbranch_execz .LBB0_1604
	v_lshl_add_u64 v[98:99], v[210:211], 2, s[12:13]
	s_waitcnt lgkmcnt(0)
	v_add_f32_e32 v96, v96, v97
	global_atomic_add_f32 v[98:99], v96, off
.LBB0_1604:
	s_or_b64 exec, exec, s[2:3]
	v_add_u32_e32 v164, 0x80, v200
	v_ashrrev_i32_e32 v165, 31, v164
	v_add_u32_e32 v160, 0x90, v200
	s_waitcnt lgkmcnt(0)
	v_lshlrev_b64 v[96:97], 12, v[164:165]
	v_ashrrev_i32_e32 v161, 31, v160
	v_lshl_add_u64 v[166:167], v[182:183], 0, v[96:97]
	v_lshlrev_b64 v[96:97], 12, v[160:161]
	v_lshl_add_u64 v[162:163], v[182:183], 0, v[96:97]
	global_load_dwordx4 v[120:123], v[166:167], off offset:16
	global_load_dwordx4 v[124:127], v[166:167], off
	global_load_dwordx4 v[112:115], v[166:167], off offset:528
	global_load_dwordx4 v[116:119], v[166:167], off offset:512
	global_load_dwordx4 v[104:107], v[162:163], off offset:16
	global_load_dwordx4 v[108:111], v[162:163], off
	global_load_dwordx4 v[96:99], v[162:163], off offset:528
	global_load_dwordx4 v[100:103], v[162:163], off offset:512
	v_pk_add_f32 v[94:95], v[94:95], v[158:159]
	v_pk_add_f32 v[92:93], v[92:93], v[156:157]
	v_pk_add_f32 v[90:91], v[90:91], v[154:155]
	v_pk_add_f32 v[88:89], v[88:89], v[152:153]
	global_store_dwordx4 v[208:209], v[92:95], off
	global_store_dwordx4 v[208:209], v[88:91], off offset:16
	v_cvt_pk_bf16_f32 v152, v92, v93
	v_mul_f32_e32 v93, v93, v93
	v_fmac_f32_e32 v93, v92, v92
	v_mul_f32_e32 v92, v95, v95
	v_cvt_pk_bf16_f32 v154, v88, v89
	v_fmac_f32_e32 v92, v94, v94
	v_mul_f32_e32 v89, v89, v89
	v_add_f32_e32 v92, v93, v92
	v_fmac_f32_e32 v89, v88, v88
	v_add_f32_e32 v88, v92, v89
	v_mul_f32_e32 v89, v91, v91
	v_fmac_f32_e32 v89, v90, v90
	v_pk_add_f32 v[86:87], v[86:87], v[150:151]
	v_pk_add_f32 v[84:85], v[84:85], v[148:149]
	v_add_f32_e32 v92, v89, v88
	v_pk_add_f32 v[88:89], v[80:81], v[144:145]
	v_mul_f32_e32 v80, v85, v85
	v_mul_f32_e32 v81, v87, v87
	v_fmac_f32_e32 v80, v84, v84
	v_fmac_f32_e32 v81, v86, v86
	v_add_f32_e32 v80, v80, v81
	v_mul_f32_e32 v81, v89, v89
	v_cvt_pk_bf16_f32 v155, v90, v91
	v_pk_add_f32 v[90:91], v[82:83], v[146:147]
	v_fmac_f32_e32 v81, v88, v88
	v_add_f32_e32 v80, v80, v81
	v_mul_f32_e32 v81, v91, v91
	v_fmac_f32_e32 v81, v90, v90
	v_add_f32_e32 v80, v81, v80
	v_add_f32_e32 v80, v92, v80
	v_mov_b32_e32 v81, v80
	s_nop 1
	v_permlane16_swap_b32_e32 v80, v81
	v_lshlrev_b64 v[168:169], 10, v[206:207]
	v_lshl_add_u64 v[168:169], v[168:169], 0, v[180:181]
	v_lshl_add_u64 v[156:157], v[168:169], 1, s[10:11]
	v_cvt_pk_bf16_f32 v153, v94, v95
	s_waitcnt lgkmcnt(0)
	v_add_f32_e32 v80, v80, v81
	v_mov_b32_e32 v81, v80
	s_nop 1
	v_permlane32_swap_b32_e32 v80, v81
	global_store_dwordx4 v[156:157], v[152:155], off
	global_store_dwordx4 v[208:209], v[84:87], off offset:512
	global_store_dwordx4 v[208:209], v[88:91], off offset:528
	v_cvt_pk_bf16_f32 v82, v84, v85
	v_cvt_pk_bf16_f32 v83, v86, v87
	v_cvt_pk_bf16_f32 v84, v88, v89
	v_cvt_pk_bf16_f32 v85, v90, v91
	global_store_dwordx4 v[156:157], v[82:85], off offset:256
	s_and_saveexec_b64 s[2:3], s[6:7]
	s_cbranch_execz .LBB0_1606
	v_lshl_add_u64 v[82:83], v[206:207], 2, s[12:13]
	s_waitcnt lgkmcnt(0)
	v_add_f32_e32 v80, v80, v81
	global_atomic_add_f32 v[82:83], v80, off
.LBB0_1606:
	s_or_b64 exec, exec, s[2:3]
	s_waitcnt lgkmcnt(0)
	v_lshlrev_b64 v[80:81], 10, v[202:203]
	v_lshl_add_u64 v[80:81], v[80:81], 0, v[180:181]
	v_pk_add_f32 v[78:79], v[78:79], v[142:143]
	v_pk_add_f32 v[76:77], v[76:77], v[140:141]
	v_pk_add_f32 v[74:75], v[74:75], v[138:139]
	v_pk_add_f32 v[72:73], v[72:73], v[136:137]
	global_store_dwordx4 v[204:205], v[76:79], off
	global_store_dwordx4 v[204:205], v[72:75], off offset:16
	v_lshl_add_u64 v[84:85], v[80:81], 1, s[10:11]
	v_cvt_pk_bf16_f32 v80, v76, v77
	v_mul_f32_e32 v77, v77, v77
	v_fmac_f32_e32 v77, v76, v76
	v_mul_f32_e32 v76, v79, v79
	v_cvt_pk_bf16_f32 v82, v72, v73
	v_fmac_f32_e32 v76, v78, v78
	v_mul_f32_e32 v73, v73, v73
	v_add_f32_e32 v76, v77, v76
	v_fmac_f32_e32 v73, v72, v72
	v_add_f32_e32 v72, v76, v73
	v_mul_f32_e32 v73, v75, v75
	v_fmac_f32_e32 v73, v74, v74
	v_pk_add_f32 v[70:71], v[70:71], v[134:135]
	v_pk_add_f32 v[68:69], v[68:69], v[132:133]
	v_add_f32_e32 v76, v73, v72
	v_pk_add_f32 v[72:73], v[64:65], v[128:129]
	v_mul_f32_e32 v64, v69, v69
	v_mul_f32_e32 v65, v71, v71
	v_fmac_f32_e32 v64, v68, v68
	v_fmac_f32_e32 v65, v70, v70
	v_add_f32_e32 v64, v64, v65
	v_mul_f32_e32 v65, v73, v73
	v_cvt_pk_bf16_f32 v83, v74, v75
	v_pk_add_f32 v[74:75], v[66:67], v[130:131]
	v_fmac_f32_e32 v65, v72, v72
	v_add_f32_e32 v64, v64, v65
	v_mul_f32_e32 v65, v75, v75
	v_fmac_f32_e32 v65, v74, v74
	v_add_f32_e32 v64, v65, v64
	v_add_f32_e32 v64, v76, v64
	v_mov_b32_e32 v65, v64
	s_nop 1
	v_permlane16_swap_b32_e32 v64, v65
	v_cvt_pk_bf16_f32 v81, v78, v79
	global_store_dwordx4 v[84:85], v[80:83], off
	global_store_dwordx4 v[204:205], v[68:71], off offset:512
	global_store_dwordx4 v[204:205], v[72:75], off offset:528
	v_cvt_pk_bf16_f32 v66, v68, v69
	v_cvt_pk_bf16_f32 v67, v70, v71
	s_waitcnt lgkmcnt(0)
	v_add_f32_e32 v64, v64, v65
	v_mov_b32_e32 v65, v64
	s_nop 1
	v_permlane32_swap_b32_e32 v64, v65
	v_cvt_pk_bf16_f32 v68, v72, v73
	v_cvt_pk_bf16_f32 v69, v74, v75
	global_store_dwordx4 v[84:85], v[66:69], off offset:256
	s_and_saveexec_b64 s[2:3], s[6:7]
	s_cbranch_execz .LBB0_1608
	v_lshl_add_u64 v[66:67], v[202:203], 2, s[12:13]
	s_waitcnt lgkmcnt(0)
	v_add_f32_e32 v64, v64, v65
	global_atomic_add_f32 v[66:67], v64, off
.LBB0_1608:
	s_or_b64 exec, exec, s[2:3]
	v_or_b32_e32 v64, 32, v164
	s_waitcnt lgkmcnt(0)
	v_ashrrev_i32_e32 v65, 31, v64
	v_lshlrev_b64 v[64:65], 12, v[64:65]
	v_add_u32_e32 v128, 0xb0, v200
	v_lshl_add_u64 v[64:65], v[182:183], 0, v[64:65]
	v_ashrrev_i32_e32 v129, 31, v128
	global_load_dwordx4 v[88:91], v[64:65], off offset:16
	global_load_dwordx4 v[92:95], v[64:65], off
	global_load_dwordx4 v[80:83], v[64:65], off offset:528
	global_load_dwordx4 v[84:87], v[64:65], off offset:512
	v_lshlrev_b64 v[64:65], 12, v[128:129]
	v_lshl_add_u64 v[130:131], v[182:183], 0, v[64:65]
	global_load_dwordx4 v[72:75], v[130:131], off offset:16
	global_load_dwordx4 v[76:79], v[130:131], off
	global_load_dwordx4 v[64:67], v[130:131], off offset:528
	global_load_dwordx4 v[68:71], v[130:131], off offset:512
	s_waitcnt vmcnt(26)
	v_pk_add_f32 v[62:63], v[62:63], v[126:127]
	v_pk_add_f32 v[60:61], v[60:61], v[124:125]
	v_pk_add_f32 v[58:59], v[58:59], v[122:123]
	v_pk_add_f32 v[56:57], v[56:57], v[120:121]
	global_store_dwordx4 v[166:167], v[60:63], off
	global_store_dwordx4 v[166:167], v[56:59], off offset:16
	v_cvt_pk_bf16_f32 v120, v60, v61
	v_mul_f32_e32 v61, v61, v61
	v_fmac_f32_e32 v61, v60, v60
	v_mul_f32_e32 v60, v63, v63
	v_cvt_pk_bf16_f32 v122, v56, v57
	v_fmac_f32_e32 v60, v62, v62
	v_mul_f32_e32 v57, v57, v57
	v_add_f32_e32 v60, v61, v60
	v_fmac_f32_e32 v57, v56, v56
	v_add_f32_e32 v56, v60, v57
	v_mul_f32_e32 v57, v59, v59
	v_fmac_f32_e32 v57, v58, v58
	s_waitcnt vmcnt(26)
	v_pk_add_f32 v[54:55], v[54:55], v[118:119]
	v_pk_add_f32 v[52:53], v[52:53], v[116:117]
	v_add_f32_e32 v60, v57, v56
	v_pk_add_f32 v[56:57], v[48:49], v[112:113]
	v_mul_f32_e32 v48, v53, v53
	v_mul_f32_e32 v49, v55, v55
	v_fmac_f32_e32 v48, v52, v52
	v_fmac_f32_e32 v49, v54, v54
	v_add_f32_e32 v48, v48, v49
	v_mul_f32_e32 v49, v57, v57
	v_cvt_pk_bf16_f32 v123, v58, v59
	v_pk_add_f32 v[58:59], v[50:51], v[114:115]
	v_fmac_f32_e32 v49, v56, v56
	v_add_f32_e32 v48, v48, v49
	v_mul_f32_e32 v49, v59, v59
	v_fmac_f32_e32 v49, v58, v58
	v_add_f32_e32 v48, v49, v48
	v_add_f32_e32 v48, v60, v48
	v_mov_b32_e32 v49, v48
	s_nop 1
	v_permlane16_swap_b32_e32 v48, v49
	v_lshlrev_b64 v[132:133], 10, v[164:165]
	v_lshl_add_u64 v[132:133], v[132:133], 0, v[180:181]
	v_lshl_add_u64 v[124:125], v[132:133], 1, s[10:11]
	v_cvt_pk_bf16_f32 v121, v62, v63
	s_waitcnt lgkmcnt(0)
	v_add_f32_e32 v48, v48, v49
	v_mov_b32_e32 v49, v48
	s_nop 1
	v_permlane32_swap_b32_e32 v48, v49
	global_store_dwordx4 v[124:125], v[120:123], off
	global_store_dwordx4 v[166:167], v[52:55], off offset:512
	global_store_dwordx4 v[166:167], v[56:59], off offset:528
	v_cvt_pk_bf16_f32 v50, v52, v53
	v_cvt_pk_bf16_f32 v51, v54, v55
	v_cvt_pk_bf16_f32 v52, v56, v57
	v_cvt_pk_bf16_f32 v53, v58, v59
	global_store_dwordx4 v[124:125], v[50:53], off offset:256
	s_and_saveexec_b64 s[2:3], s[6:7]
	s_cbranch_execz .LBB0_1610
	v_lshl_add_u64 v[50:51], v[164:165], 2, s[12:13]
	s_waitcnt lgkmcnt(0)
	v_add_f32_e32 v48, v48, v49
	global_atomic_add_f32 v[50:51], v48, off
.LBB0_1610:
	s_or_b64 exec, exec, s[2:3]
	s_waitcnt lgkmcnt(0)
	v_lshlrev_b64 v[48:49], 10, v[160:161]
	v_lshl_add_u64 v[48:49], v[48:49], 0, v[180:181]
	s_waitcnt vmcnt(28)
	v_pk_add_f32 v[46:47], v[46:47], v[110:111]
	v_pk_add_f32 v[44:45], v[44:45], v[108:109]
	v_pk_add_f32 v[42:43], v[42:43], v[106:107]
	v_pk_add_f32 v[40:41], v[40:41], v[104:105]
	global_store_dwordx4 v[162:163], v[44:47], off
	global_store_dwordx4 v[162:163], v[40:43], off offset:16
	v_lshl_add_u64 v[52:53], v[48:49], 1, s[10:11]
	v_cvt_pk_bf16_f32 v48, v44, v45
	v_mul_f32_e32 v45, v45, v45
	v_fmac_f32_e32 v45, v44, v44
	v_mul_f32_e32 v44, v47, v47
	v_cvt_pk_bf16_f32 v50, v40, v41
	v_fmac_f32_e32 v44, v46, v46
	v_mul_f32_e32 v41, v41, v41
	v_add_f32_e32 v44, v45, v44
	v_fmac_f32_e32 v41, v40, v40
	v_add_f32_e32 v40, v44, v41
	v_mul_f32_e32 v41, v43, v43
	v_fmac_f32_e32 v41, v42, v42
	s_waitcnt vmcnt(28)
	v_pk_add_f32 v[38:39], v[38:39], v[102:103]
	v_pk_add_f32 v[36:37], v[36:37], v[100:101]
	v_add_f32_e32 v44, v41, v40
	v_pk_add_f32 v[40:41], v[32:33], v[96:97]
	v_mul_f32_e32 v32, v37, v37
	v_mul_f32_e32 v33, v39, v39
	v_fmac_f32_e32 v32, v36, v36
	v_fmac_f32_e32 v33, v38, v38
	v_add_f32_e32 v32, v32, v33
	v_mul_f32_e32 v33, v41, v41
	v_cvt_pk_bf16_f32 v51, v42, v43
	v_pk_add_f32 v[42:43], v[34:35], v[98:99]
	v_fmac_f32_e32 v33, v40, v40
	v_add_f32_e32 v32, v32, v33
	v_mul_f32_e32 v33, v43, v43
	v_fmac_f32_e32 v33, v42, v42
	v_add_f32_e32 v32, v33, v32
	v_add_f32_e32 v32, v44, v32
	v_mov_b32_e32 v33, v32
	s_nop 1
	v_permlane16_swap_b32_e32 v32, v33
	v_cvt_pk_bf16_f32 v49, v46, v47
	global_store_dwordx4 v[52:53], v[48:51], off
	global_store_dwordx4 v[162:163], v[36:39], off offset:512
	global_store_dwordx4 v[162:163], v[40:43], off offset:528
	v_cvt_pk_bf16_f32 v34, v36, v37
	v_cvt_pk_bf16_f32 v35, v38, v39
	s_waitcnt lgkmcnt(0)
	v_add_f32_e32 v32, v32, v33
	v_mov_b32_e32 v33, v32
	s_nop 1
	v_permlane32_swap_b32_e32 v32, v33
	v_cvt_pk_bf16_f32 v36, v40, v41
	v_cvt_pk_bf16_f32 v37, v42, v43
	global_store_dwordx4 v[52:53], v[34:37], off offset:256
	s_and_saveexec_b64 s[2:3], s[6:7]
	s_cbranch_execz .LBB0_1612
	v_lshl_add_u64 v[34:35], v[160:161], 2, s[12:13]
	s_waitcnt lgkmcnt(0)
	v_add_f32_e32 v32, v32, v33
	global_atomic_add_f32 v[34:35], v32, off
.LBB0_1612:
	s_or_b64 exec, exec, s[2:3]
	v_add_u32_e32 v32, 0xa0, v200
	s_waitcnt lgkmcnt(0)
	v_ashrrev_i32_e32 v33, 31, v32
	v_lshlrev_b64 v[34:35], 10, v[32:33]
	v_lshlrev_b64 v[36:37], 12, v[32:33]
	v_lshl_add_u64 v[34:35], v[34:35], 0, v[180:181]
	s_waitcnt vmcnt(18)
	v_pk_add_f32 v[30:31], v[30:31], v[94:95]
	v_pk_add_f32 v[28:29], v[28:29], v[92:93]
	v_lshl_add_u64 v[38:39], v[182:183], 0, v[36:37]
	v_pk_add_f32 v[26:27], v[26:27], v[90:91]
	v_pk_add_f32 v[24:25], v[24:25], v[88:89]
	global_store_dwordx4 v[38:39], v[28:31], off
	global_store_dwordx4 v[38:39], v[24:27], off offset:16
	v_lshl_add_u64 v[40:41], v[34:35], 1, s[10:11]
	v_cvt_pk_bf16_f32 v34, v28, v29
	v_mul_f32_e32 v29, v29, v29
	v_fmac_f32_e32 v29, v28, v28
	v_mul_f32_e32 v28, v31, v31
	v_cvt_pk_bf16_f32 v36, v24, v25
	v_fmac_f32_e32 v28, v30, v30
	v_mul_f32_e32 v25, v25, v25
	v_add_f32_e32 v28, v29, v28
	v_fmac_f32_e32 v25, v24, v24
	v_add_f32_e32 v24, v28, v25
	v_mul_f32_e32 v25, v27, v27
	v_fmac_f32_e32 v25, v26, v26
	s_waitcnt vmcnt(18)
	v_pk_add_f32 v[22:23], v[22:23], v[86:87]
	v_pk_add_f32 v[20:21], v[20:21], v[84:85]
	v_add_f32_e32 v28, v25, v24
	v_pk_add_f32 v[24:25], v[16:17], v[80:81]
	v_mul_f32_e32 v16, v21, v21
	v_mul_f32_e32 v17, v23, v23
	v_fmac_f32_e32 v16, v20, v20
	v_fmac_f32_e32 v17, v22, v22
	v_add_f32_e32 v16, v16, v17
	v_mul_f32_e32 v17, v25, v25
	v_cvt_pk_bf16_f32 v37, v26, v27
	v_pk_add_f32 v[26:27], v[18:19], v[82:83]
	v_fmac_f32_e32 v17, v24, v24
	v_add_f32_e32 v16, v16, v17
	v_mul_f32_e32 v17, v27, v27
	v_fmac_f32_e32 v17, v26, v26
	v_add_f32_e32 v16, v17, v16
	v_add_f32_e32 v16, v28, v16
	v_mov_b32_e32 v17, v16
	s_nop 1
	v_permlane16_swap_b32_e32 v16, v17
	v_cvt_pk_bf16_f32 v35, v30, v31
	global_store_dwordx4 v[40:41], v[34:37], off
	global_store_dwordx4 v[38:39], v[20:23], off offset:512
	global_store_dwordx4 v[38:39], v[24:27], off offset:528
	v_cvt_pk_bf16_f32 v18, v20, v21
	v_cvt_pk_bf16_f32 v19, v22, v23
	s_waitcnt lgkmcnt(0)
	v_add_f32_e32 v16, v16, v17
	v_mov_b32_e32 v17, v16
	s_nop 1
	v_permlane32_swap_b32_e32 v16, v17
	v_cvt_pk_bf16_f32 v20, v24, v25
	v_cvt_pk_bf16_f32 v21, v26, v27
	global_store_dwordx4 v[40:41], v[18:21], off offset:256
	s_and_saveexec_b64 s[2:3], s[6:7]
	s_cbranch_execz .LBB0_1614
	v_lshl_add_u64 v[18:19], v[32:33], 2, s[12:13]
	s_waitcnt lgkmcnt(0)
	v_add_f32_e32 v16, v16, v17
	global_atomic_add_f32 v[18:19], v16, off
.LBB0_1614:
	s_or_b64 exec, exec, s[2:3]
	s_waitcnt lgkmcnt(0)
	v_lshlrev_b64 v[16:17], 10, v[128:129]
	v_lshl_add_u64 v[16:17], v[16:17], 0, v[180:181]
	s_waitcnt vmcnt(20)
	v_pk_add_f32 v[14:15], v[14:15], v[78:79]
	v_pk_add_f32 v[12:13], v[12:13], v[76:77]
	v_pk_add_f32 v[10:11], v[10:11], v[74:75]
	v_pk_add_f32 v[8:9], v[8:9], v[72:73]
	global_store_dwordx4 v[130:131], v[12:15], off
	global_store_dwordx4 v[130:131], v[8:11], off offset:16
	v_lshl_add_u64 v[20:21], v[16:17], 1, s[10:11]
	v_cvt_pk_bf16_f32 v16, v12, v13
	v_mul_f32_e32 v13, v13, v13
	v_fmac_f32_e32 v13, v12, v12
	v_mul_f32_e32 v12, v15, v15
	v_cvt_pk_bf16_f32 v18, v8, v9
	v_fmac_f32_e32 v12, v14, v14
	v_mul_f32_e32 v9, v9, v9
	v_add_f32_e32 v12, v13, v12
	v_fmac_f32_e32 v9, v8, v8
	v_add_f32_e32 v8, v12, v9
	v_mul_f32_e32 v9, v11, v11
	v_fmac_f32_e32 v9, v10, v10
	s_waitcnt vmcnt(20)
	v_pk_add_f32 v[6:7], v[6:7], v[70:71]
	v_pk_add_f32 v[4:5], v[4:5], v[68:69]
	v_add_f32_e32 v12, v9, v8
	v_pk_add_f32 v[8:9], v[0:1], v[64:65]
	v_mul_f32_e32 v0, v5, v5
	v_mul_f32_e32 v1, v7, v7
	v_fmac_f32_e32 v0, v4, v4
	v_fmac_f32_e32 v1, v6, v6
	v_add_f32_e32 v0, v0, v1
	v_mul_f32_e32 v1, v9, v9
	v_cvt_pk_bf16_f32 v19, v10, v11
	v_pk_add_f32 v[10:11], v[2:3], v[66:67]
	v_fmac_f32_e32 v1, v8, v8
	v_add_f32_e32 v0, v0, v1
	v_mul_f32_e32 v1, v11, v11
	v_fmac_f32_e32 v1, v10, v10
	v_add_f32_e32 v0, v1, v0
	v_add_f32_e32 v0, v12, v0
	v_mov_b32_e32 v1, v0
	s_nop 1
	v_permlane16_swap_b32_e32 v0, v1
	v_cvt_pk_bf16_f32 v17, v14, v15
	global_store_dwordx4 v[20:21], v[16:19], off
	global_store_dwordx4 v[130:131], v[4:7], off offset:512
	global_store_dwordx4 v[130:131], v[8:11], off offset:528
	v_cvt_pk_bf16_f32 v2, v4, v5
	v_cvt_pk_bf16_f32 v3, v6, v7
	s_waitcnt lgkmcnt(0)
	v_add_f32_e32 v0, v0, v1
	v_mov_b32_e32 v1, v0
	s_nop 1
	v_permlane32_swap_b32_e32 v0, v1
	v_cvt_pk_bf16_f32 v4, v8, v9
	v_cvt_pk_bf16_f32 v5, v10, v11
	global_store_dwordx4 v[20:21], v[2:5], off offset:256
	s_and_saveexec_b64 s[2:3], s[6:7]
	s_cbranch_execz .LBB0_1616
	v_lshl_add_u64 v[2:3], v[128:129], 2, s[12:13]
	s_waitcnt lgkmcnt(0)
	v_add_f32_e32 v0, v0, v1
	global_atomic_add_f32 v[2:3], v0, off

.LBB0_1830:
	v_lshl_add_u32 v200, s0, 8, v193
	v_lshl_or_b32 v180, s33, 8, v215
	v_ashrrev_i32_e32 v181, 31, v180
	v_ashrrev_i32_e32 v201, 31, v200
	v_lshl_add_u64 v[182:183], v[180:181], 2, s[16:17]
	v_lshlrev_b64 v[128:129], 12, v[200:201]
	v_lshl_add_u64 v[224:225], v[182:183], 0, v[128:129]
	global_load_dwordx4 v[220:223], v[224:225], off
	global_load_dwordx4 v[234:237], v[224:225], off offset:16
	global_load_dwordx4 v[238:241], v[224:225], off offset:512
	global_load_dwordx4 v[242:245], v[224:225], off offset:528
	v_or_b32_e32 v210, 16, v200
	v_or_b32_e32 v206, 32, v200
	v_or_b32_e32 v202, 48, v200
	v_ashrrev_i32_e32 v211, 31, v210
	v_ashrrev_i32_e32 v207, 31, v206
	v_ashrrev_i32_e32 v203, 31, v202
	v_lshlrev_b64 v[128:129], 12, v[210:211]
	v_lshlrev_b64 v[130:131], 12, v[206:207]
	v_lshlrev_b64 v[132:133], 12, v[202:203]
	v_lshl_add_u64 v[212:213], v[182:183], 0, v[128:129]
	v_lshl_add_u64 v[208:209], v[182:183], 0, v[130:131]
	v_lshl_add_u64 v[204:205], v[182:183], 0, v[132:133]
	global_load_dwordx4 v[168:171], v[212:213], off offset:16
	global_load_dwordx4 v[172:175], v[212:213], off
	global_load_dwordx4 v[160:163], v[212:213], off offset:528
	global_load_dwordx4 v[164:167], v[212:213], off offset:512
	global_load_dwordx4 v[152:155], v[208:209], off offset:16
	global_load_dwordx4 v[156:159], v[208:209], off
	global_load_dwordx4 v[144:147], v[208:209], off offset:528
	global_load_dwordx4 v[148:151], v[208:209], off offset:512
	global_load_dwordx4 v[136:139], v[204:205], off offset:16
	global_load_dwordx4 v[140:143], v[204:205], off
	global_load_dwordx4 v[128:131], v[204:205], off offset:528
	global_load_dwordx4 v[132:135], v[204:205], off offset:512
	v_and_b32_e32 v218, 64, v233
	v_xor_b32_e32 v217, 16, v233
	v_add_u32_e32 v218, 64, v218
	v_xor_b32_e32 v219, 32, v233
	v_cmp_lt_i32_e32 vcc, v217, v218
	v_lshlrev_b64 v[246:247], 10, v[200:201]
	v_lshl_add_u64 v[246:247], v[246:247], 0, v[180:181]
	v_cndmask_b32_e32 v217, v233, v217, vcc
	v_cmp_lt_i32_e32 vcc, v219, v218
	v_lshlrev_b32_e32 v218, 2, v217
	v_lshl_add_u64 v[246:247], v[246:247], 1, s[22:23]
	v_cndmask_b32_e32 v219, v233, v219, vcc
	v_lshlrev_b32_e32 v217, 2, v219
	s_waitcnt vmcnt(0)
	v_pk_add_f32 v[126:127], v[126:127], v[222:223]
	v_pk_add_f32 v[124:125], v[124:125], v[220:221]
	v_pk_add_f32 v[118:119], v[118:119], v[240:241]
	v_pk_add_f32 v[116:117], v[116:117], v[238:239]
	v_pk_add_f32 v[122:123], v[122:123], v[236:237]
	v_pk_add_f32 v[120:121], v[120:121], v[234:235]
	v_pk_add_f32 v[220:221], v[112:113], v[242:243]
	global_store_dwordx4 v[224:225], v[124:127], off
	global_store_dwordx4 v[224:225], v[120:123], off offset:16
	v_cvt_pk_bf16_f32 v112, v124, v125
	v_cvt_pk_bf16_f32 v113, v126, v127
	v_mul_f32_e32 v125, v125, v125
	v_mul_f32_e32 v127, v127, v127
	v_mul_f32_e32 v219, v117, v117
	v_mul_f32_e32 v234, v119, v119
	v_pk_add_f32 v[222:223], v[114:115], v[244:245]
	v_cvt_pk_bf16_f32 v114, v120, v121
	v_cvt_pk_bf16_f32 v115, v122, v123
	v_mul_f32_e32 v121, v121, v121
	v_mul_f32_e32 v123, v123, v123
	v_mul_f32_e32 v235, v221, v221
	v_fmac_f32_e32 v125, v124, v124
	v_fmac_f32_e32 v127, v126, v126
	v_fmac_f32_e32 v219, v116, v116
	v_fmac_f32_e32 v234, v118, v118
	v_mul_f32_e32 v236, v223, v223
	v_fmac_f32_e32 v121, v120, v120
	v_fmac_f32_e32 v123, v122, v122
	v_fmac_f32_e32 v235, v220, v220
	v_add_f32_e32 v120, v125, v127
	v_add_f32_e32 v122, v219, v234
	v_fmac_f32_e32 v236, v222, v222
	v_add_f32_e32 v120, v120, v121
	v_add_f32_e32 v121, v122, v235
	v_add_f32_e32 v120, v123, v120
	v_add_f32_e32 v121, v236, v121
	v_add_f32_e32 v120, v120, v121
	v_mov_b32_e32 v121, v120
	s_nop 1
	v_permlane16_swap_b32_e32 v120, v121
	global_store_dwordx4 v[246:247], v[112:115], off
	global_store_dwordx4 v[224:225], v[116:119], off offset:512
	global_store_dwordx4 v[224:225], v[220:223], off offset:528
	v_cvt_pk_bf16_f32 v114, v116, v117
	v_cvt_pk_bf16_f32 v115, v118, v119
	v_cvt_pk_bf16_f32 v116, v220, v221
	s_waitcnt lgkmcnt(0)
	v_add_f32_e32 v112, v120, v121
	v_mov_b32_e32 v113, v112
	s_nop 1
	v_permlane32_swap_b32_e32 v112, v113
	v_cvt_pk_bf16_f32 v117, v222, v223
	global_store_dwordx4 v[246:247], v[114:117], off offset:256
	s_and_saveexec_b64 s[2:3], s[6:7]
	s_cbranch_execz .LBB0_1832
	v_lshl_add_u64 v[114:115], v[200:201], 2, s[24:25]
	s_waitcnt lgkmcnt(0)
	v_add_f32_e32 v112, v112, v113
	global_atomic_add_f32 v[114:115], v112, off
.LBB0_1832:
	s_or_b64 exec, exec, s[2:3]
	s_waitcnt lgkmcnt(0)
	v_lshlrev_b64 v[112:113], 10, v[210:211]
	v_lshl_add_u64 v[112:113], v[112:113], 0, v[180:181]
	v_pk_add_f32 v[110:111], v[110:111], v[174:175]
	v_pk_add_f32 v[108:109], v[108:109], v[172:173]
	v_pk_add_f32 v[106:107], v[106:107], v[170:171]
	v_pk_add_f32 v[104:105], v[104:105], v[168:169]
	global_store_dwordx4 v[212:213], v[108:111], off
	global_store_dwordx4 v[212:213], v[104:107], off offset:16
	v_lshl_add_u64 v[116:117], v[112:113], 1, s[22:23]
	v_cvt_pk_bf16_f32 v112, v108, v109
	v_mul_f32_e32 v109, v109, v109
	v_fmac_f32_e32 v109, v108, v108
	v_mul_f32_e32 v108, v111, v111
	v_cvt_pk_bf16_f32 v114, v104, v105
	v_fmac_f32_e32 v108, v110, v110
	v_mul_f32_e32 v105, v105, v105
	v_add_f32_e32 v108, v109, v108
	v_fmac_f32_e32 v105, v104, v104
	v_add_f32_e32 v104, v108, v105
	v_mul_f32_e32 v105, v107, v107
	v_fmac_f32_e32 v105, v106, v106
	v_pk_add_f32 v[102:103], v[102:103], v[166:167]
	v_pk_add_f32 v[100:101], v[100:101], v[164:165]
	v_add_f32_e32 v108, v105, v104
	v_pk_add_f32 v[104:105], v[96:97], v[160:161]
	v_mul_f32_e32 v96, v101, v101
	v_mul_f32_e32 v97, v103, v103
	v_fmac_f32_e32 v96, v100, v100
	v_fmac_f32_e32 v97, v102, v102
	v_add_f32_e32 v96, v96, v97
	v_mul_f32_e32 v97, v105, v105
	v_cvt_pk_bf16_f32 v115, v106, v107
	v_pk_add_f32 v[106:107], v[98:99], v[162:163]
	v_fmac_f32_e32 v97, v104, v104
	v_add_f32_e32 v96, v96, v97
	v_mul_f32_e32 v97, v107, v107
	v_fmac_f32_e32 v97, v106, v106
	v_add_f32_e32 v96, v97, v96
	v_add_f32_e32 v96, v108, v96
	v_mov_b32_e32 v97, v96
	s_nop 1
	v_permlane16_swap_b32_e32 v96, v97
	v_cvt_pk_bf16_f32 v113, v110, v111
	global_store_dwordx4 v[116:117], v[112:115], off
	global_store_dwordx4 v[212:213], v[100:103], off offset:512
	global_store_dwordx4 v[212:213], v[104:107], off offset:528
	v_cvt_pk_bf16_f32 v98, v100, v101
	v_cvt_pk_bf16_f32 v99, v102, v103
	s_waitcnt lgkmcnt(0)
	v_add_f32_e32 v96, v96, v97
	v_mov_b32_e32 v97, v96
	s_nop 1
	v_permlane32_swap_b32_e32 v96, v97
	v_cvt_pk_bf16_f32 v100, v104, v105
	v_cvt_pk_bf16_f32 v101, v106, v107
	global_store_dwordx4 v[116:117], v[98:101], off offset:256
	s_and_saveexec_b64 s[2:3], s[6:7]
	s_cbranch_execz .LBB0_1834
	v_lshl_add_u64 v[98:99], v[210:211], 2, s[24:25]
	s_waitcnt lgkmcnt(0)
	v_add_f32_e32 v96, v96, v97
	global_atomic_add_f32 v[98:99], v96, off
.LBB0_1834:
	s_or_b64 exec, exec, s[2:3]
	v_add_u32_e32 v164, 0x80, v200
	v_ashrrev_i32_e32 v165, 31, v164
	v_add_u32_e32 v160, 0x90, v200
	s_waitcnt lgkmcnt(0)
	v_lshlrev_b64 v[96:97], 12, v[164:165]
	v_ashrrev_i32_e32 v161, 31, v160
	v_lshl_add_u64 v[166:167], v[182:183], 0, v[96:97]
	v_lshlrev_b64 v[96:97], 12, v[160:161]
	v_lshl_add_u64 v[162:163], v[182:183], 0, v[96:97]
	global_load_dwordx4 v[120:123], v[166:167], off offset:16
	global_load_dwordx4 v[124:127], v[166:167], off
	global_load_dwordx4 v[112:115], v[166:167], off offset:528
	global_load_dwordx4 v[116:119], v[166:167], off offset:512
	global_load_dwordx4 v[104:107], v[162:163], off offset:16
	global_load_dwordx4 v[108:111], v[162:163], off
	global_load_dwordx4 v[96:99], v[162:163], off offset:528
	global_load_dwordx4 v[100:103], v[162:163], off offset:512
	v_pk_add_f32 v[94:95], v[94:95], v[158:159]
	v_pk_add_f32 v[92:93], v[92:93], v[156:157]
	v_pk_add_f32 v[90:91], v[90:91], v[154:155]
	v_pk_add_f32 v[88:89], v[88:89], v[152:153]
	global_store_dwordx4 v[208:209], v[92:95], off
	global_store_dwordx4 v[208:209], v[88:91], off offset:16
	v_cvt_pk_bf16_f32 v152, v92, v93
	v_mul_f32_e32 v93, v93, v93
	v_fmac_f32_e32 v93, v92, v92
	v_mul_f32_e32 v92, v95, v95
	v_cvt_pk_bf16_f32 v154, v88, v89
	v_fmac_f32_e32 v92, v94, v94
	v_mul_f32_e32 v89, v89, v89
	v_add_f32_e32 v92, v93, v92
	v_fmac_f32_e32 v89, v88, v88
	v_add_f32_e32 v88, v92, v89
	v_mul_f32_e32 v89, v91, v91
	v_fmac_f32_e32 v89, v90, v90
	v_pk_add_f32 v[86:87], v[86:87], v[150:151]
	v_pk_add_f32 v[84:85], v[84:85], v[148:149]
	v_add_f32_e32 v92, v89, v88
	v_pk_add_f32 v[88:89], v[80:81], v[144:145]
	v_mul_f32_e32 v80, v85, v85
	v_mul_f32_e32 v81, v87, v87
	v_fmac_f32_e32 v80, v84, v84
	v_fmac_f32_e32 v81, v86, v86
	v_add_f32_e32 v80, v80, v81
	v_mul_f32_e32 v81, v89, v89
	v_cvt_pk_bf16_f32 v155, v90, v91
	v_pk_add_f32 v[90:91], v[82:83], v[146:147]
	v_fmac_f32_e32 v81, v88, v88
	v_add_f32_e32 v80, v80, v81
	v_mul_f32_e32 v81, v91, v91
	v_fmac_f32_e32 v81, v90, v90
	v_add_f32_e32 v80, v81, v80
	v_add_f32_e32 v80, v92, v80
	v_mov_b32_e32 v81, v80
	s_nop 1
	v_permlane16_swap_b32_e32 v80, v81
	v_lshlrev_b64 v[168:169], 10, v[206:207]
	v_lshl_add_u64 v[168:169], v[168:169], 0, v[180:181]
	v_lshl_add_u64 v[156:157], v[168:169], 1, s[22:23]
	v_cvt_pk_bf16_f32 v153, v94, v95
	s_waitcnt lgkmcnt(0)
	v_add_f32_e32 v80, v80, v81
	v_mov_b32_e32 v81, v80
	s_nop 1
	v_permlane32_swap_b32_e32 v80, v81
	global_store_dwordx4 v[156:157], v[152:155], off
	global_store_dwordx4 v[208:209], v[84:87], off offset:512
	global_store_dwordx4 v[208:209], v[88:91], off offset:528
	v_cvt_pk_bf16_f32 v82, v84, v85
	v_cvt_pk_bf16_f32 v83, v86, v87
	v_cvt_pk_bf16_f32 v84, v88, v89
	v_cvt_pk_bf16_f32 v85, v90, v91
	global_store_dwordx4 v[156:157], v[82:85], off offset:256
	s_and_saveexec_b64 s[2:3], s[6:7]
	s_cbranch_execz .LBB0_1836
	v_lshl_add_u64 v[82:83], v[206:207], 2, s[24:25]
	s_waitcnt lgkmcnt(0)
	v_add_f32_e32 v80, v80, v81
	global_atomic_add_f32 v[82:83], v80, off
.LBB0_1836:
	s_or_b64 exec, exec, s[2:3]
	s_waitcnt lgkmcnt(0)
	v_lshlrev_b64 v[80:81], 10, v[202:203]
	v_lshl_add_u64 v[80:81], v[80:81], 0, v[180:181]
	v_pk_add_f32 v[78:79], v[78:79], v[142:143]
	v_pk_add_f32 v[76:77], v[76:77], v[140:141]
	v_pk_add_f32 v[74:75], v[74:75], v[138:139]
	v_pk_add_f32 v[72:73], v[72:73], v[136:137]
	global_store_dwordx4 v[204:205], v[76:79], off
	global_store_dwordx4 v[204:205], v[72:75], off offset:16
	v_lshl_add_u64 v[84:85], v[80:81], 1, s[22:23]
	v_cvt_pk_bf16_f32 v80, v76, v77
	v_mul_f32_e32 v77, v77, v77
	v_fmac_f32_e32 v77, v76, v76
	v_mul_f32_e32 v76, v79, v79
	v_cvt_pk_bf16_f32 v82, v72, v73
	v_fmac_f32_e32 v76, v78, v78
	v_mul_f32_e32 v73, v73, v73
	v_add_f32_e32 v76, v77, v76
	v_fmac_f32_e32 v73, v72, v72
	v_add_f32_e32 v72, v76, v73
	v_mul_f32_e32 v73, v75, v75
	v_fmac_f32_e32 v73, v74, v74
	v_pk_add_f32 v[70:71], v[70:71], v[134:135]
	v_pk_add_f32 v[68:69], v[68:69], v[132:133]
	v_add_f32_e32 v76, v73, v72
	v_pk_add_f32 v[72:73], v[64:65], v[128:129]
	v_mul_f32_e32 v64, v69, v69
	v_mul_f32_e32 v65, v71, v71
	v_fmac_f32_e32 v64, v68, v68
	v_fmac_f32_e32 v65, v70, v70
	v_add_f32_e32 v64, v64, v65
	v_mul_f32_e32 v65, v73, v73
	v_cvt_pk_bf16_f32 v83, v74, v75
	v_pk_add_f32 v[74:75], v[66:67], v[130:131]
	v_fmac_f32_e32 v65, v72, v72
	v_add_f32_e32 v64, v64, v65
	v_mul_f32_e32 v65, v75, v75
	v_fmac_f32_e32 v65, v74, v74
	v_add_f32_e32 v64, v65, v64
	v_add_f32_e32 v64, v76, v64
	v_mov_b32_e32 v65, v64
	s_nop 1
	v_permlane16_swap_b32_e32 v64, v65
	v_cvt_pk_bf16_f32 v81, v78, v79
	global_store_dwordx4 v[84:85], v[80:83], off
	global_store_dwordx4 v[204:205], v[68:71], off offset:512
	global_store_dwordx4 v[204:205], v[72:75], off offset:528
	v_cvt_pk_bf16_f32 v66, v68, v69
	v_cvt_pk_bf16_f32 v67, v70, v71
	s_waitcnt lgkmcnt(0)
	v_add_f32_e32 v64, v64, v65
	v_mov_b32_e32 v65, v64
	s_nop 1
	v_permlane32_swap_b32_e32 v64, v65
	v_cvt_pk_bf16_f32 v68, v72, v73
	v_cvt_pk_bf16_f32 v69, v74, v75
	global_store_dwordx4 v[84:85], v[66:69], off offset:256
	s_and_saveexec_b64 s[2:3], s[6:7]
	s_cbranch_execz .LBB0_1838
	v_lshl_add_u64 v[66:67], v[202:203], 2, s[24:25]
	s_waitcnt lgkmcnt(0)
	v_add_f32_e32 v64, v64, v65
	global_atomic_add_f32 v[66:67], v64, off
.LBB0_1838:
	s_or_b64 exec, exec, s[2:3]
	v_or_b32_e32 v64, 32, v164
	s_waitcnt lgkmcnt(0)
	v_ashrrev_i32_e32 v65, 31, v64
	v_lshlrev_b64 v[64:65], 12, v[64:65]
	v_add_u32_e32 v128, 0xb0, v200
	v_lshl_add_u64 v[64:65], v[182:183], 0, v[64:65]
	v_ashrrev_i32_e32 v129, 31, v128
	global_load_dwordx4 v[88:91], v[64:65], off offset:16
	global_load_dwordx4 v[92:95], v[64:65], off
	global_load_dwordx4 v[80:83], v[64:65], off offset:528
	global_load_dwordx4 v[84:87], v[64:65], off offset:512
	v_lshlrev_b64 v[64:65], 12, v[128:129]
	v_lshl_add_u64 v[130:131], v[182:183], 0, v[64:65]
	global_load_dwordx4 v[72:75], v[130:131], off offset:16
	global_load_dwordx4 v[76:79], v[130:131], off
	global_load_dwordx4 v[64:67], v[130:131], off offset:528
	global_load_dwordx4 v[68:71], v[130:131], off offset:512
	s_waitcnt vmcnt(26)
	v_pk_add_f32 v[62:63], v[62:63], v[126:127]
	v_pk_add_f32 v[60:61], v[60:61], v[124:125]
	v_pk_add_f32 v[58:59], v[58:59], v[122:123]
	v_pk_add_f32 v[56:57], v[56:57], v[120:121]
	global_store_dwordx4 v[166:167], v[60:63], off
	global_store_dwordx4 v[166:167], v[56:59], off offset:16
	v_cvt_pk_bf16_f32 v120, v60, v61
	v_mul_f32_e32 v61, v61, v61
	v_fmac_f32_e32 v61, v60, v60
	v_mul_f32_e32 v60, v63, v63
	v_cvt_pk_bf16_f32 v122, v56, v57
	v_fmac_f32_e32 v60, v62, v62
	v_mul_f32_e32 v57, v57, v57
	v_add_f32_e32 v60, v61, v60
	v_fmac_f32_e32 v57, v56, v56
	v_add_f32_e32 v56, v60, v57
	v_mul_f32_e32 v57, v59, v59
	v_fmac_f32_e32 v57, v58, v58
	s_waitcnt vmcnt(26)
	v_pk_add_f32 v[54:55], v[54:55], v[118:119]
	v_pk_add_f32 v[52:53], v[52:53], v[116:117]
	v_add_f32_e32 v60, v57, v56
	v_pk_add_f32 v[56:57], v[48:49], v[112:113]
	v_mul_f32_e32 v48, v53, v53
	v_mul_f32_e32 v49, v55, v55
	v_fmac_f32_e32 v48, v52, v52
	v_fmac_f32_e32 v49, v54, v54
	v_add_f32_e32 v48, v48, v49
	v_mul_f32_e32 v49, v57, v57
	v_cvt_pk_bf16_f32 v123, v58, v59
	v_pk_add_f32 v[58:59], v[50:51], v[114:115]
	v_fmac_f32_e32 v49, v56, v56
	v_add_f32_e32 v48, v48, v49
	v_mul_f32_e32 v49, v59, v59
	v_fmac_f32_e32 v49, v58, v58
	v_add_f32_e32 v48, v49, v48
	v_add_f32_e32 v48, v60, v48
	v_mov_b32_e32 v49, v48
	s_nop 1
	v_permlane16_swap_b32_e32 v48, v49
	v_lshlrev_b64 v[132:133], 10, v[164:165]
	v_lshl_add_u64 v[132:133], v[132:133], 0, v[180:181]
	v_lshl_add_u64 v[124:125], v[132:133], 1, s[22:23]
	v_cvt_pk_bf16_f32 v121, v62, v63
	s_waitcnt lgkmcnt(0)
	v_add_f32_e32 v48, v48, v49
	v_mov_b32_e32 v49, v48
	s_nop 1
	v_permlane32_swap_b32_e32 v48, v49
	global_store_dwordx4 v[124:125], v[120:123], off
	global_store_dwordx4 v[166:167], v[52:55], off offset:512
	global_store_dwordx4 v[166:167], v[56:59], off offset:528
	v_cvt_pk_bf16_f32 v50, v52, v53
	v_cvt_pk_bf16_f32 v51, v54, v55
	v_cvt_pk_bf16_f32 v52, v56, v57
	v_cvt_pk_bf16_f32 v53, v58, v59
	global_store_dwordx4 v[124:125], v[50:53], off offset:256
	s_and_saveexec_b64 s[2:3], s[6:7]
	s_cbranch_execz .LBB0_1840
	v_lshl_add_u64 v[50:51], v[164:165], 2, s[24:25]
	s_waitcnt lgkmcnt(0)
	v_add_f32_e32 v48, v48, v49
	global_atomic_add_f32 v[50:51], v48, off
.LBB0_1840:
	s_or_b64 exec, exec, s[2:3]
	s_waitcnt lgkmcnt(0)
	v_lshlrev_b64 v[48:49], 10, v[160:161]
	v_lshl_add_u64 v[48:49], v[48:49], 0, v[180:181]
	s_waitcnt vmcnt(28)
	v_pk_add_f32 v[46:47], v[46:47], v[110:111]
	v_pk_add_f32 v[44:45], v[44:45], v[108:109]
	v_pk_add_f32 v[42:43], v[42:43], v[106:107]
	v_pk_add_f32 v[40:41], v[40:41], v[104:105]
	global_store_dwordx4 v[162:163], v[44:47], off
	global_store_dwordx4 v[162:163], v[40:43], off offset:16
	v_lshl_add_u64 v[52:53], v[48:49], 1, s[22:23]
	v_cvt_pk_bf16_f32 v48, v44, v45
	v_mul_f32_e32 v45, v45, v45
	v_fmac_f32_e32 v45, v44, v44
	v_mul_f32_e32 v44, v47, v47
	v_cvt_pk_bf16_f32 v50, v40, v41
	v_fmac_f32_e32 v44, v46, v46
	v_mul_f32_e32 v41, v41, v41
	v_add_f32_e32 v44, v45, v44
	v_fmac_f32_e32 v41, v40, v40
	v_add_f32_e32 v40, v44, v41
	v_mul_f32_e32 v41, v43, v43
	v_fmac_f32_e32 v41, v42, v42
	s_waitcnt vmcnt(28)
	v_pk_add_f32 v[38:39], v[38:39], v[102:103]
	v_pk_add_f32 v[36:37], v[36:37], v[100:101]
	v_add_f32_e32 v44, v41, v40
	v_pk_add_f32 v[40:41], v[32:33], v[96:97]
	v_mul_f32_e32 v32, v37, v37
	v_mul_f32_e32 v33, v39, v39
	v_fmac_f32_e32 v32, v36, v36
	v_fmac_f32_e32 v33, v38, v38
	v_add_f32_e32 v32, v32, v33
	v_mul_f32_e32 v33, v41, v41
	v_cvt_pk_bf16_f32 v51, v42, v43
	v_pk_add_f32 v[42:43], v[34:35], v[98:99]
	v_fmac_f32_e32 v33, v40, v40
	v_add_f32_e32 v32, v32, v33
	v_mul_f32_e32 v33, v43, v43
	v_fmac_f32_e32 v33, v42, v42
	v_add_f32_e32 v32, v33, v32
	v_add_f32_e32 v32, v44, v32
	v_mov_b32_e32 v33, v32
	s_nop 1
	v_permlane16_swap_b32_e32 v32, v33
	v_cvt_pk_bf16_f32 v49, v46, v47
	global_store_dwordx4 v[52:53], v[48:51], off
	global_store_dwordx4 v[162:163], v[36:39], off offset:512
	global_store_dwordx4 v[162:163], v[40:43], off offset:528
	v_cvt_pk_bf16_f32 v34, v36, v37
	v_cvt_pk_bf16_f32 v35, v38, v39
	s_waitcnt lgkmcnt(0)
	v_add_f32_e32 v32, v32, v33
	v_mov_b32_e32 v33, v32
	s_nop 1
	v_permlane32_swap_b32_e32 v32, v33
	v_cvt_pk_bf16_f32 v36, v40, v41
	v_cvt_pk_bf16_f32 v37, v42, v43
	global_store_dwordx4 v[52:53], v[34:37], off offset:256
	s_and_saveexec_b64 s[2:3], s[6:7]
	s_cbranch_execz .LBB0_1842
	v_lshl_add_u64 v[34:35], v[160:161], 2, s[24:25]
	s_waitcnt lgkmcnt(0)
	v_add_f32_e32 v32, v32, v33
	global_atomic_add_f32 v[34:35], v32, off
.LBB0_1842:
	s_or_b64 exec, exec, s[2:3]
	v_add_u32_e32 v32, 0xa0, v200
	s_waitcnt lgkmcnt(0)
	v_ashrrev_i32_e32 v33, 31, v32
	v_lshlrev_b64 v[34:35], 10, v[32:33]
	v_lshlrev_b64 v[36:37], 12, v[32:33]
	v_lshl_add_u64 v[34:35], v[34:35], 0, v[180:181]
	s_waitcnt vmcnt(18)
	v_pk_add_f32 v[30:31], v[30:31], v[94:95]
	v_pk_add_f32 v[28:29], v[28:29], v[92:93]
	v_lshl_add_u64 v[38:39], v[182:183], 0, v[36:37]
	v_pk_add_f32 v[26:27], v[26:27], v[90:91]
	v_pk_add_f32 v[24:25], v[24:25], v[88:89]
	global_store_dwordx4 v[38:39], v[28:31], off
	global_store_dwordx4 v[38:39], v[24:27], off offset:16
	v_lshl_add_u64 v[40:41], v[34:35], 1, s[22:23]
	v_cvt_pk_bf16_f32 v34, v28, v29
	v_mul_f32_e32 v29, v29, v29
	v_fmac_f32_e32 v29, v28, v28
	v_mul_f32_e32 v28, v31, v31
	v_cvt_pk_bf16_f32 v36, v24, v25
	v_fmac_f32_e32 v28, v30, v30
	v_mul_f32_e32 v25, v25, v25
	v_add_f32_e32 v28, v29, v28
	v_fmac_f32_e32 v25, v24, v24
	v_add_f32_e32 v24, v28, v25
	v_mul_f32_e32 v25, v27, v27
	v_fmac_f32_e32 v25, v26, v26
	s_waitcnt vmcnt(18)
	v_pk_add_f32 v[22:23], v[22:23], v[86:87]
	v_pk_add_f32 v[20:21], v[20:21], v[84:85]
	v_add_f32_e32 v28, v25, v24
	v_pk_add_f32 v[24:25], v[16:17], v[80:81]
	v_mul_f32_e32 v16, v21, v21
	v_mul_f32_e32 v17, v23, v23
	v_fmac_f32_e32 v16, v20, v20
	v_fmac_f32_e32 v17, v22, v22
	v_add_f32_e32 v16, v16, v17
	v_mul_f32_e32 v17, v25, v25
	v_cvt_pk_bf16_f32 v37, v26, v27
	v_pk_add_f32 v[26:27], v[18:19], v[82:83]
	v_fmac_f32_e32 v17, v24, v24
	v_add_f32_e32 v16, v16, v17
	v_mul_f32_e32 v17, v27, v27
	v_fmac_f32_e32 v17, v26, v26
	v_add_f32_e32 v16, v17, v16
	v_add_f32_e32 v16, v28, v16
	v_mov_b32_e32 v17, v16
	s_nop 1
	v_permlane16_swap_b32_e32 v16, v17
	v_cvt_pk_bf16_f32 v35, v30, v31
	global_store_dwordx4 v[40:41], v[34:37], off
	global_store_dwordx4 v[38:39], v[20:23], off offset:512
	global_store_dwordx4 v[38:39], v[24:27], off offset:528
	v_cvt_pk_bf16_f32 v18, v20, v21
	v_cvt_pk_bf16_f32 v19, v22, v23
	s_waitcnt lgkmcnt(0)
	v_add_f32_e32 v16, v16, v17
	v_mov_b32_e32 v17, v16
	s_nop 1
	v_permlane32_swap_b32_e32 v16, v17
	v_cvt_pk_bf16_f32 v20, v24, v25
	v_cvt_pk_bf16_f32 v21, v26, v27
	global_store_dwordx4 v[40:41], v[18:21], off offset:256
	s_and_saveexec_b64 s[2:3], s[6:7]
	s_cbranch_execz .LBB0_1844
	v_lshl_add_u64 v[18:19], v[32:33], 2, s[24:25]
	s_waitcnt lgkmcnt(0)
	v_add_f32_e32 v16, v16, v17
	global_atomic_add_f32 v[18:19], v16, off
.LBB0_1844:
	s_or_b64 exec, exec, s[2:3]
	s_waitcnt lgkmcnt(0)
	v_lshlrev_b64 v[16:17], 10, v[128:129]
	v_lshl_add_u64 v[16:17], v[16:17], 0, v[180:181]
	s_waitcnt vmcnt(20)
	v_pk_add_f32 v[14:15], v[14:15], v[78:79]
	v_pk_add_f32 v[12:13], v[12:13], v[76:77]
	v_pk_add_f32 v[10:11], v[10:11], v[74:75]
	v_pk_add_f32 v[8:9], v[8:9], v[72:73]
	global_store_dwordx4 v[130:131], v[12:15], off
	global_store_dwordx4 v[130:131], v[8:11], off offset:16
	v_lshl_add_u64 v[20:21], v[16:17], 1, s[22:23]
	v_cvt_pk_bf16_f32 v16, v12, v13
	v_mul_f32_e32 v13, v13, v13
	v_fmac_f32_e32 v13, v12, v12
	v_mul_f32_e32 v12, v15, v15
	v_cvt_pk_bf16_f32 v18, v8, v9
	v_fmac_f32_e32 v12, v14, v14
	v_mul_f32_e32 v9, v9, v9
	v_add_f32_e32 v12, v13, v12
	v_fmac_f32_e32 v9, v8, v8
	v_add_f32_e32 v8, v12, v9
	v_mul_f32_e32 v9, v11, v11
	v_fmac_f32_e32 v9, v10, v10
	s_waitcnt vmcnt(20)
	v_pk_add_f32 v[6:7], v[6:7], v[70:71]
	v_pk_add_f32 v[4:5], v[4:5], v[68:69]
	v_add_f32_e32 v12, v9, v8
	v_pk_add_f32 v[8:9], v[0:1], v[64:65]
	v_mul_f32_e32 v0, v5, v5
	v_mul_f32_e32 v1, v7, v7
	v_fmac_f32_e32 v0, v4, v4
	v_fmac_f32_e32 v1, v6, v6
	v_add_f32_e32 v0, v0, v1
	v_mul_f32_e32 v1, v9, v9
	v_cvt_pk_bf16_f32 v19, v10, v11
	v_pk_add_f32 v[10:11], v[2:3], v[66:67]
	v_fmac_f32_e32 v1, v8, v8
	v_add_f32_e32 v0, v0, v1
	v_mul_f32_e32 v1, v11, v11
	v_fmac_f32_e32 v1, v10, v10
	v_add_f32_e32 v0, v1, v0
	v_add_f32_e32 v0, v12, v0
	v_mov_b32_e32 v1, v0
	s_nop 1
	v_permlane16_swap_b32_e32 v0, v1
	v_cvt_pk_bf16_f32 v17, v14, v15
	global_store_dwordx4 v[20:21], v[16:19], off
	global_store_dwordx4 v[130:131], v[4:7], off offset:512
	global_store_dwordx4 v[130:131], v[8:11], off offset:528
	v_cvt_pk_bf16_f32 v2, v4, v5
	v_cvt_pk_bf16_f32 v3, v6, v7
	s_waitcnt lgkmcnt(0)
	v_add_f32_e32 v0, v0, v1
	v_mov_b32_e32 v1, v0
	s_nop 1
	v_permlane32_swap_b32_e32 v0, v1
	v_cvt_pk_bf16_f32 v4, v8, v9
	v_cvt_pk_bf16_f32 v5, v10, v11
	global_store_dwordx4 v[20:21], v[2:5], off offset:256
	s_and_saveexec_b64 s[2:3], s[6:7]
	s_cbranch_execz .LBB0_1846
	v_lshl_add_u64 v[2:3], v[128:129], 2, s[24:25]
	s_waitcnt lgkmcnt(0)
	v_add_f32_e32 v0, v0, v1
	global_atomic_add_f32 v[2:3], v0, off

.LBB0_2004:
	v_mul_f32_e32 v125, v125, v125
	v_fmac_f32_e32 v125, v124, v124
	v_mul_f32_e32 v124, v127, v127
	v_fmac_f32_e32 v124, v126, v126
	v_mul_f32_e32 v121, v121, v121
	v_mul_f32_e32 v117, v117, v117
	v_add_f32_e32 v124, v125, v124
	v_fmac_f32_e32 v121, v120, v120
	v_fmac_f32_e32 v117, v116, v116
	v_mul_f32_e32 v116, v119, v119
	v_add_f32_e32 v120, v124, v121
	v_mul_f32_e32 v121, v123, v123
	v_fmac_f32_e32 v116, v118, v118
	v_mul_f32_e32 v113, v113, v113
	v_fmac_f32_e32 v121, v122, v122
	v_and_b32_e32 v122, 64, v233
	v_add_f32_e32 v116, v117, v116
	v_fmac_f32_e32 v113, v112, v112
	v_add_f32_e32 v120, v121, v120
	v_xor_b32_e32 v121, 16, v233
	v_add_u32_e32 v122, 64, v122
	v_add_f32_e32 v112, v116, v113
	v_mul_f32_e32 v113, v115, v115
	v_cmp_lt_i32_e32 vcc, v121, v122
	v_fmac_f32_e32 v113, v114, v114
	v_add_f32_e32 v112, v113, v112
	v_cndmask_b32_e32 v121, v233, v121, vcc
	v_lshlrev_b32_e32 v178, 2, v121
	v_add_f32_e32 v112, v120, v112
	v_mov_b32_e32 v113, v112
	s_nop 1
	v_permlane16_swap_b32_e32 v112, v113
	v_xor_b32_e32 v114, 32, v233
	v_cmp_lt_i32_e32 vcc, v114, v122
	v_lshl_add_u64 v[176:177], v[208:209], 2, s[24:25]
	s_waitcnt lgkmcnt(0)
	v_add_f32_e32 v112, v112, v113
	v_cndmask_b32_e32 v114, v233, v114, vcc
	v_lshlrev_b32_e32 v179, 2, v114
	v_mov_b32_e32 v113, v112
	s_nop 1
	v_permlane32_swap_b32_e32 v112, v113
	s_and_saveexec_b64 s[2:3], s[6:7]
	s_cbranch_execz .LBB0_2006
	s_waitcnt lgkmcnt(0)
	v_add_f32_e32 v112, v112, v113
	global_atomic_add_f32 v[176:177], v112, off

.LBB0_2010:
	v_mul_f32_e32 v109, v109, v109
	v_mul_f32_e32 v101, v101, v101
	v_fmac_f32_e32 v109, v108, v108
	v_mul_f32_e32 v108, v111, v111
	v_fmac_f32_e32 v101, v100, v100
	v_mul_f32_e32 v100, v103, v103
	v_fmac_f32_e32 v108, v110, v110
	v_mul_f32_e32 v105, v105, v105
	v_fmac_f32_e32 v100, v102, v102
	v_mul_f32_e32 v97, v97, v97
	v_add_f32_e32 v108, v109, v108
	v_fmac_f32_e32 v105, v104, v104
	v_add_f32_e32 v100, v101, v100
	v_fmac_f32_e32 v97, v96, v96
	v_add_f32_e32 v104, v108, v105
	v_mul_f32_e32 v105, v107, v107
	v_add_f32_e32 v96, v100, v97
	v_mul_f32_e32 v97, v99, v99
	v_fmac_f32_e32 v105, v106, v106
	v_fmac_f32_e32 v97, v98, v98
	v_add_f32_e32 v104, v105, v104
	v_add_f32_e32 v96, v97, v96
	v_add_f32_e32 v96, v104, v96
	v_mov_b32_e32 v97, v96
	s_nop 1
	v_permlane16_swap_b32_e32 v96, v97
	s_waitcnt lgkmcnt(0)
	v_add_f32_e32 v96, v96, v97
	v_mov_b32_e32 v97, v96
	s_nop 1
	v_permlane32_swap_b32_e32 v96, v97
	s_and_saveexec_b64 s[2:3], s[6:7]
	s_cbranch_execz .LBB0_2012
	s_waitcnt lgkmcnt(0)
	v_add_f32_e32 v96, v96, v97
	global_atomic_add_f32 v[176:177], v96, off offset:64

.LBB0_2016:
	v_mul_f32_e32 v93, v93, v93
	v_mul_f32_e32 v85, v85, v85
	v_fmac_f32_e32 v93, v92, v92
	v_mul_f32_e32 v92, v95, v95
	v_fmac_f32_e32 v85, v84, v84
	v_mul_f32_e32 v84, v87, v87
	v_fmac_f32_e32 v92, v94, v94
	v_mul_f32_e32 v89, v89, v89
	v_fmac_f32_e32 v84, v86, v86
	v_mul_f32_e32 v81, v81, v81
	v_add_f32_e32 v92, v93, v92
	v_fmac_f32_e32 v89, v88, v88
	v_add_f32_e32 v84, v85, v84
	v_fmac_f32_e32 v81, v80, v80
	v_add_f32_e32 v88, v92, v89
	v_mul_f32_e32 v89, v91, v91
	v_add_f32_e32 v80, v84, v81
	v_mul_f32_e32 v81, v83, v83
	v_fmac_f32_e32 v89, v90, v90
	v_fmac_f32_e32 v81, v82, v82
	v_add_f32_e32 v88, v89, v88
	v_add_f32_e32 v80, v81, v80
	v_add_f32_e32 v80, v88, v80
	v_mov_b32_e32 v81, v80
	s_nop 1
	v_permlane16_swap_b32_e32 v80, v81
	s_waitcnt lgkmcnt(0)
	v_add_f32_e32 v80, v80, v81
	v_mov_b32_e32 v81, v80
	s_nop 1
	v_permlane32_swap_b32_e32 v80, v81
	s_and_saveexec_b64 s[2:3], s[6:7]
	s_cbranch_execz .LBB0_2018
	s_waitcnt lgkmcnt(0)
	v_add_f32_e32 v80, v80, v81
	global_atomic_add_f32 v[176:177], v80, off offset:128

.LBB0_2022:
	v_mul_f32_e32 v77, v77, v77
	v_mul_f32_e32 v69, v69, v69
	v_fmac_f32_e32 v77, v76, v76
	v_mul_f32_e32 v76, v79, v79
	v_fmac_f32_e32 v69, v68, v68
	v_mul_f32_e32 v68, v71, v71
	v_fmac_f32_e32 v76, v78, v78
	v_mul_f32_e32 v73, v73, v73
	v_fmac_f32_e32 v68, v70, v70
	v_mul_f32_e32 v65, v65, v65
	v_add_f32_e32 v76, v77, v76
	v_fmac_f32_e32 v73, v72, v72
	v_add_f32_e32 v68, v69, v68
	v_fmac_f32_e32 v65, v64, v64
	v_add_f32_e32 v72, v76, v73
	v_mul_f32_e32 v73, v75, v75
	v_add_f32_e32 v64, v68, v65
	v_mul_f32_e32 v65, v67, v67
	v_fmac_f32_e32 v73, v74, v74
	v_fmac_f32_e32 v65, v66, v66
	v_add_f32_e32 v72, v73, v72
	v_add_f32_e32 v64, v65, v64
	v_add_f32_e32 v64, v72, v64
	v_mov_b32_e32 v65, v64
	s_nop 1
	v_permlane16_swap_b32_e32 v64, v65
	s_waitcnt lgkmcnt(0)
	v_add_f32_e32 v64, v64, v65
	v_mov_b32_e32 v65, v64
	s_nop 1
	v_permlane32_swap_b32_e32 v64, v65
	s_and_saveexec_b64 s[2:3], s[6:7]
	s_cbranch_execz .LBB0_2024
	s_waitcnt lgkmcnt(0)
	v_add_f32_e32 v64, v64, v65
	global_atomic_add_f32 v[176:177], v64, off offset:192

.LBB0_2028:
	v_mul_f32_e32 v61, v61, v61
	v_mul_f32_e32 v53, v53, v53
	v_fmac_f32_e32 v61, v60, v60
	v_mul_f32_e32 v60, v63, v63
	v_fmac_f32_e32 v53, v52, v52
	v_mul_f32_e32 v52, v55, v55
	v_fmac_f32_e32 v60, v62, v62
	v_mul_f32_e32 v57, v57, v57
	v_fmac_f32_e32 v52, v54, v54
	v_mul_f32_e32 v49, v49, v49
	v_add_f32_e32 v60, v61, v60
	v_fmac_f32_e32 v57, v56, v56
	v_add_f32_e32 v52, v53, v52
	v_fmac_f32_e32 v49, v48, v48
	v_add_f32_e32 v56, v60, v57
	v_mul_f32_e32 v57, v59, v59
	v_add_f32_e32 v48, v52, v49
	v_mul_f32_e32 v49, v51, v51
	v_fmac_f32_e32 v57, v58, v58
	v_fmac_f32_e32 v49, v50, v50
	v_add_f32_e32 v56, v57, v56
	v_add_f32_e32 v48, v49, v48
	v_add_f32_e32 v48, v56, v48
	v_mov_b32_e32 v49, v48
	s_nop 1
	v_permlane16_swap_b32_e32 v48, v49
	s_waitcnt lgkmcnt(0)
	v_add_f32_e32 v48, v48, v49
	v_mov_b32_e32 v49, v48
	s_nop 1
	v_permlane32_swap_b32_e32 v48, v49
	s_and_saveexec_b64 s[2:3], s[6:7]
	s_cbranch_execz .LBB0_2030
	s_waitcnt lgkmcnt(0)
	v_add_f32_e32 v48, v48, v49
	global_atomic_add_f32 v[176:177], v48, off offset:512

.LBB0_2034:
	v_mul_f32_e32 v45, v45, v45
	v_mul_f32_e32 v37, v37, v37
	v_fmac_f32_e32 v45, v44, v44
	v_mul_f32_e32 v44, v47, v47
	v_fmac_f32_e32 v37, v36, v36
	v_mul_f32_e32 v36, v39, v39
	v_fmac_f32_e32 v44, v46, v46
	v_mul_f32_e32 v41, v41, v41
	v_fmac_f32_e32 v36, v38, v38
	v_mul_f32_e32 v33, v33, v33
	v_add_f32_e32 v44, v45, v44
	v_fmac_f32_e32 v41, v40, v40
	v_add_f32_e32 v36, v37, v36
	v_fmac_f32_e32 v33, v32, v32
	v_add_f32_e32 v40, v44, v41
	v_mul_f32_e32 v41, v43, v43
	v_add_f32_e32 v32, v36, v33
	v_mul_f32_e32 v33, v35, v35
	v_fmac_f32_e32 v41, v42, v42
	v_fmac_f32_e32 v33, v34, v34
	v_add_f32_e32 v40, v41, v40
	v_add_f32_e32 v32, v33, v32
	v_add_f32_e32 v32, v40, v32
	v_mov_b32_e32 v33, v32
	s_nop 1
	v_permlane16_swap_b32_e32 v32, v33
	s_waitcnt lgkmcnt(0)
	v_add_f32_e32 v32, v32, v33
	v_mov_b32_e32 v33, v32
	s_nop 1
	v_permlane32_swap_b32_e32 v32, v33
	s_and_saveexec_b64 s[2:3], s[6:7]
	s_cbranch_execz .LBB0_2036
	s_waitcnt lgkmcnt(0)
	v_add_f32_e32 v32, v32, v33
	global_atomic_add_f32 v[176:177], v32, off offset:576

.LBB0_2040:
	v_mul_f32_e32 v29, v29, v29
	v_mul_f32_e32 v21, v21, v21
	v_fmac_f32_e32 v29, v28, v28
	v_mul_f32_e32 v28, v31, v31
	v_fmac_f32_e32 v21, v20, v20
	v_mul_f32_e32 v20, v23, v23
	v_fmac_f32_e32 v28, v30, v30
	v_mul_f32_e32 v25, v25, v25
	v_fmac_f32_e32 v20, v22, v22
	v_mul_f32_e32 v17, v17, v17
	v_add_f32_e32 v28, v29, v28
	v_fmac_f32_e32 v25, v24, v24
	v_add_f32_e32 v20, v21, v20
	v_fmac_f32_e32 v17, v16, v16
	v_add_f32_e32 v24, v28, v25
	v_mul_f32_e32 v25, v27, v27
	v_add_f32_e32 v16, v20, v17
	v_mul_f32_e32 v17, v19, v19
	v_fmac_f32_e32 v25, v26, v26
	v_fmac_f32_e32 v17, v18, v18
	v_add_f32_e32 v24, v25, v24
	v_add_f32_e32 v16, v17, v16
	v_add_f32_e32 v16, v24, v16
	v_mov_b32_e32 v17, v16
	s_nop 1
	v_permlane16_swap_b32_e32 v16, v17
	s_waitcnt lgkmcnt(0)
	v_add_f32_e32 v16, v16, v17
	v_mov_b32_e32 v17, v16
	s_nop 1
	v_permlane32_swap_b32_e32 v16, v17
	s_and_saveexec_b64 s[2:3], s[6:7]
	s_cbranch_execz .LBB0_2042
	s_waitcnt lgkmcnt(0)
	v_add_f32_e32 v16, v16, v17
	global_atomic_add_f32 v[176:177], v16, off offset:640

.LBB0_2046:
	v_mul_f32_e32 v13, v13, v13
	v_mul_f32_e32 v5, v5, v5
	v_fmac_f32_e32 v13, v12, v12
	v_mul_f32_e32 v12, v15, v15
	v_fmac_f32_e32 v5, v4, v4
	v_mul_f32_e32 v4, v7, v7
	v_fmac_f32_e32 v12, v14, v14
	v_mul_f32_e32 v9, v9, v9
	v_fmac_f32_e32 v4, v6, v6
	v_mul_f32_e32 v1, v1, v1
	v_add_f32_e32 v12, v13, v12
	v_fmac_f32_e32 v9, v8, v8
	v_add_f32_e32 v4, v5, v4
	v_fmac_f32_e32 v1, v0, v0
	v_add_f32_e32 v8, v12, v9
	v_mul_f32_e32 v9, v11, v11
	v_add_f32_e32 v0, v4, v1
	v_mul_f32_e32 v1, v3, v3
	v_fmac_f32_e32 v9, v10, v10
	v_fmac_f32_e32 v1, v2, v2
	v_add_f32_e32 v8, v9, v8
	v_add_f32_e32 v0, v1, v0
	v_add_f32_e32 v0, v8, v0
	v_mov_b32_e32 v1, v0
	s_nop 1
	v_permlane16_swap_b32_e32 v0, v1
	s_waitcnt lgkmcnt(0)
	v_add_f32_e32 v0, v0, v1
	v_mov_b32_e32 v1, v0
	s_nop 1
	v_permlane32_swap_b32_e32 v0, v1
	s_and_saveexec_b64 s[2:3], s[6:7]
	s_cbranch_execz .LBB0_2048
	s_waitcnt lgkmcnt(0)
	v_add_f32_e32 v0, v0, v1
	global_atomic_add_f32 v[176:177], v0, off offset:704
